# GEMM epilogue output stores made write-through (sc1) so the phase-end L2 writeback is short; V^T rounds reversed
# baseline (speedup 1.0000x reference)
.LBB0_42:
	s_lshl_b32 s21, s46, 12
	s_and_b32 s21, s21, 0x1000
	v_add_u32_e32 v159, s21, v163
	ds_read_b128 v[142:145], v159
	v_lshl_add_u32 v158, s33, 8, v160
	s_mov_b64 s[28:29], 0x1000000
	s_mov_b32 s63, 0x40000
	s_mov_b32 s64, 0x48000
	s_waitcnt lgkmcnt(0)
	v_add_f32_e32 v146, v142, v143
	v_add_f32_e32 v147, v144, v145
	ds_read_b128 v[142:145], v159 offset:16
	v_add_f32_e32 v154, v146, v147
	s_mov_b32 s67, 0x50000
	s_waitcnt lgkmcnt(0)
	v_add_f32_e32 v148, v142, v143
	v_add_f32_e32 v149, v144, v145
	ds_read_b128 v[142:145], v159 offset:32
	s_waitcnt lgkmcnt(0)
	v_add_f32_e32 v150, v142, v143
	v_add_f32_e32 v151, v144, v145
	ds_read_b128 v[142:145], v159 offset:48
	s_waitcnt lgkmcnt(0)
	v_add_f32_e32 v152, v142, v143
	v_add_f32_e32 v153, v144, v145
	ds_read_b128 v[142:145], v159 offset:64
	s_waitcnt lgkmcnt(0)
	v_add_f32_e32 v155, v142, v143
	v_add_f32_e32 v156, v144, v145
	ds_read_b128 v[144:147], v159 offset:80
	v_fmamk_f32 v142, v154, 0x3a800000, v191
	v_add_f32_e32 v143, v148, v149
	v_fmamk_f32 v143, v143, 0x3a800000, v191
	v_rsq_f32_e32 v142, v142
	s_waitcnt lgkmcnt(0)
	v_add_f32_e32 v154, v144, v145
	v_add_f32_e32 v157, v146, v147
	ds_read_b128 v[146:149], v159 offset:96
	v_add_f32_e32 v145, v152, v153
	v_add_f32_e32 v152, v155, v156
	v_add_f32_e32 v144, v150, v151
	v_fmamk_f32 v144, v144, 0x3a800000, v191
	s_waitcnt lgkmcnt(0)
	v_add_f32_e32 v165, v146, v147
	v_add_f32_e32 v166, v148, v149
	ds_read_b128 v[146:149], v159 offset:112
	v_fmamk_f32 v145, v145, 0x3a800000, v191
	v_rsq_f32_e32 v143, v143
	v_rsq_f32_e32 v144, v144
	v_rsq_f32_e32 v145, v145
	s_waitcnt lgkmcnt(0)
	v_add_f32_e32 v155, v146, v147
	v_add_f32_e32 v156, v148, v149
	ds_read_b128 v[148:151], v159 offset:2048
	v_add_f32_e32 v147, v154, v157
	v_fmamk_f32 v146, v152, 0x3a800000, v191
	v_fmamk_f32 v147, v147, 0x3a800000, v191
	v_rsq_f32_e32 v146, v146
	s_waitcnt lgkmcnt(0)
	v_add_f32_e32 v154, v148, v149
	v_add_f32_e32 v157, v150, v151
	ds_read_b128 v[150:153], v159 offset:2064
	v_add_f32_e32 v148, v165, v166
	v_add_f32_e32 v149, v155, v156
	v_add_f32_e32 v156, v154, v157
	v_rsq_f32_e32 v147, v147
	s_waitcnt lgkmcnt(0)
	v_add_f32_e32 v165, v150, v151
	v_add_f32_e32 v166, v152, v153
	ds_read_b128 v[150:153], v159 offset:2080
	v_fmamk_f32 v148, v148, 0x3a800000, v191
	v_fmamk_f32 v149, v149, 0x3a800000, v191
	v_rsq_f32_e32 v148, v148
	v_rsq_f32_e32 v149, v149
	s_waitcnt lgkmcnt(0)
	v_add_f32_e32 v167, v150, v151
	v_add_f32_e32 v168, v152, v153
	ds_read_b128 v[152:155], v159 offset:2096
	v_add_f32_e32 v151, v165, v166
	v_fmamk_f32 v150, v156, 0x3a800000, v191
	v_fmamk_f32 v151, v151, 0x3a800000, v191
	v_rsq_f32_e32 v150, v150
	s_waitcnt lgkmcnt(0)
	v_add_f32_e32 v153, v152, v153
	v_add_f32_e32 v165, v154, v155
	ds_read_b128 v[154:157], v159 offset:2112
	v_add_f32_e32 v152, v167, v168
	v_add_f32_e32 v153, v153, v165
	v_fmamk_f32 v152, v152, 0x3a800000, v191
	v_fmamk_f32 v153, v153, 0x3a800000, v191
	s_waitcnt lgkmcnt(0)
	v_add_f32_e32 v166, v154, v155
	v_add_f32_e32 v167, v156, v157
	ds_read_b128 v[154:157], v159 offset:2128
	v_add_f32_e32 v165, v166, v167
	v_rsq_f32_e32 v151, v151
	v_rsq_f32_e32 v152, v152
	v_rsq_f32_e32 v153, v153
	s_waitcnt lgkmcnt(0)
	v_add_f32_e32 v155, v154, v155
	v_add_f32_e32 v156, v156, v157
	ds_read_b128 v[166:169], v159 offset:2144
	v_add_f32_e32 v155, v155, v156
	v_fmamk_f32 v154, v165, 0x3a800000, v191
	v_fmamk_f32 v155, v155, 0x3a800000, v191
	v_rsq_f32_e32 v154, v154
	s_waitcnt lgkmcnt(0)
	v_add_f32_e32 v156, v166, v167
	v_add_f32_e32 v157, v168, v169
	ds_read_b128 v[166:169], v159 offset:2160
	v_add_f32_e32 v156, v156, v157
	v_fmamk_f32 v156, v156, 0x3a800000, v191
	v_rsq_f32_e32 v155, v155
	v_rsq_f32_e32 v156, v156
	s_waitcnt lgkmcnt(0)
	v_add_f32_e32 v157, v166, v167
	v_add_f32_e32 v159, v168, v169
	v_lshl_or_b32 v166, s4, 8, v162
	v_add_f32_e32 v157, v157, v159
	v_fmamk_f32 v157, v157, 0x3a800000, v191
	v_rsq_f32_e32 v157, v157
	v_ashrrev_i32_e32 v159, 31, v158
	v_pk_mul_f32 v[122:123], v[122:123], v[142:143]
	v_pk_mul_f32 v[124:125], v[124:125], v[144:145]
	v_pk_mul_f32 v[114:115], v[114:115], v[146:147]
	v_ashrrev_i32_e32 v167, 31, v166
	v_lshlrev_b64 v[168:169], 17, v[158:159]
	v_cvt_pk_bf16_f32 v122, v122, v123
	v_cvt_pk_bf16_f32 v123, v124, v125
	v_cvt_pk_bf16_f32 v124, v114, v115
	v_pk_mul_f32 v[114:115], v[116:117], v[148:149]
	v_lshlrev_b64 v[166:167], 1, v[166:167]
	v_cvt_pk_bf16_f32 v125, v114, v115
	v_lshl_add_u64 v[114:115], s[16:17], 0, v[168:169]
	v_lshl_add_u64 v[114:115], v[114:115], 0, v[166:167]
	global_store_dwordx4 v[114:115], v[122:125], off sc1
	v_pk_mul_f32 v[116:117], v[126:127], v[150:151]
	v_pk_mul_f32 v[118:119], v[118:119], v[154:155]
	v_pk_mul_f32 v[122:123], v[128:129], v[152:153]
	v_pk_mul_f32 v[120:121], v[120:121], v[156:157]
	v_cvt_pk_bf16_f32 v116, v116, v117
	v_cvt_pk_bf16_f32 v117, v122, v123
	v_cvt_pk_bf16_f32 v118, v118, v119
	v_cvt_pk_bf16_f32 v119, v120, v121
	global_store_dwordx4 v[114:115], v[116:119], off offset:256 sc1
	v_pk_mul_f32 v[102:103], v[102:103], v[142:143]
	v_pk_mul_f32 v[104:105], v[104:105], v[144:145]
	v_or_b32_e32 v116, 16, v158
	v_ashrrev_i32_e32 v117, 31, v116
	v_pk_mul_f32 v[98:99], v[98:99], v[146:147]
	v_lshlrev_b64 v[116:117], 17, v[116:117]
	v_cvt_pk_bf16_f32 v102, v102, v103
	v_cvt_pk_bf16_f32 v103, v104, v105
	v_cvt_pk_bf16_f32 v104, v98, v99
	v_pk_mul_f32 v[98:99], v[100:101], v[148:149]
	v_pk_mul_f32 v[100:101], v[112:113], v[152:153]
	v_cvt_pk_bf16_f32 v105, v98, v99
	v_lshl_add_u64 v[98:99], s[16:17], 0, v[116:117]
	v_lshl_add_u64 v[116:117], v[98:99], 0, v[166:167]
	v_pk_mul_f32 v[98:99], v[110:111], v[150:151]
	global_store_dwordx4 v[116:117], v[102:105], off sc1
	v_cvt_pk_bf16_f32 v98, v98, v99
	v_cvt_pk_bf16_f32 v99, v100, v101
	v_pk_mul_f32 v[100:101], v[106:107], v[154:155]
	v_pk_mul_f32 v[102:103], v[108:109], v[156:157]
	v_cvt_pk_bf16_f32 v100, v100, v101
	v_cvt_pk_bf16_f32 v101, v102, v103
	global_store_dwordx4 v[116:117], v[98:101], off offset:256 sc1
	v_pk_mul_f32 v[86:87], v[86:87], v[142:143]
	v_pk_mul_f32 v[88:89], v[88:89], v[144:145]
	v_or_b32_e32 v98, 32, v158
	v_ashrrev_i32_e32 v99, 31, v98
	v_pk_mul_f32 v[82:83], v[82:83], v[146:147]
	v_lshlrev_b64 v[98:99], 17, v[98:99]
	v_cvt_pk_bf16_f32 v86, v86, v87
	v_cvt_pk_bf16_f32 v87, v88, v89
	v_cvt_pk_bf16_f32 v88, v82, v83
	v_pk_mul_f32 v[82:83], v[84:85], v[148:149]
	v_pk_mul_f32 v[84:85], v[96:97], v[152:153]
	v_cvt_pk_bf16_f32 v89, v82, v83
	v_lshl_add_u64 v[82:83], s[16:17], 0, v[98:99]
	v_lshl_add_u64 v[98:99], v[82:83], 0, v[166:167]
	v_pk_mul_f32 v[82:83], v[94:95], v[150:151]
	global_store_dwordx4 v[98:99], v[86:89], off sc1
	v_cvt_pk_bf16_f32 v82, v82, v83
	v_cvt_pk_bf16_f32 v83, v84, v85
	v_pk_mul_f32 v[84:85], v[90:91], v[154:155]
	v_pk_mul_f32 v[86:87], v[92:93], v[156:157]
	v_cvt_pk_bf16_f32 v84, v84, v85
	v_cvt_pk_bf16_f32 v85, v86, v87
	global_store_dwordx4 v[98:99], v[82:85], off offset:256 sc1
	v_pk_mul_f32 v[54:55], v[54:55], v[142:143]
	v_pk_mul_f32 v[56:57], v[56:57], v[144:145]
	v_or_b32_e32 v82, 48, v158
	v_ashrrev_i32_e32 v83, 31, v82
	v_pk_mul_f32 v[50:51], v[50:51], v[146:147]
	v_lshlrev_b64 v[82:83], 17, v[82:83]
	v_cvt_pk_bf16_f32 v54, v54, v55
	v_cvt_pk_bf16_f32 v55, v56, v57
	v_cvt_pk_bf16_f32 v56, v50, v51
	v_pk_mul_f32 v[50:51], v[52:53], v[148:149]
	v_pk_mul_f32 v[52:53], v[80:81], v[152:153]
	v_cvt_pk_bf16_f32 v57, v50, v51
	v_lshl_add_u64 v[50:51], s[16:17], 0, v[82:83]
	v_lshl_add_u64 v[82:83], v[50:51], 0, v[166:167]
	v_pk_mul_f32 v[50:51], v[78:79], v[150:151]
	s_mov_b32 s4, 0x1000000
	global_store_dwordx4 v[82:83], v[54:57], off sc1
	v_cvt_pk_bf16_f32 v50, v50, v51
	v_cvt_pk_bf16_f32 v51, v52, v53
	v_pk_mul_f32 v[52:53], v[70:71], v[154:155]
	v_pk_mul_f32 v[54:55], v[72:73], v[156:157]
	v_add_co_u32_e32 v56, vcc, s4, v114
	v_pk_mul_f32 v[36:37], v[36:37], v[142:143]
	v_pk_mul_f32 v[38:39], v[38:39], v[144:145]
	v_pk_mul_f32 v[32:33], v[32:33], v[146:147]
	v_cvt_pk_bf16_f32 v52, v52, v53
	v_cvt_pk_bf16_f32 v53, v54, v55
	v_addc_co_u32_e32 v57, vcc, 0, v115, vcc
	v_cvt_pk_bf16_f32 v36, v36, v37
	v_cvt_pk_bf16_f32 v37, v38, v39
	v_cvt_pk_bf16_f32 v38, v32, v33
	v_pk_mul_f32 v[32:33], v[34:35], v[148:149]
	s_mov_b32 s4, 0x1200000
	global_store_dwordx4 v[82:83], v[50:53], off offset:256 sc1
	v_cvt_pk_bf16_f32 v39, v32, v33
	v_add_co_u32_e32 v32, vcc, s4, v114
	v_pk_mul_f32 v[50:51], v[62:63], v[142:143]
	v_pk_mul_f32 v[52:53], v[64:65], v[144:145]
	v_pk_mul_f32 v[20:21], v[20:21], v[142:143]
	v_pk_mul_f32 v[22:23], v[22:23], v[144:145]
	v_pk_mul_f32 v[16:17], v[16:17], v[146:147]
	v_cvt_pk_bf16_f32 v50, v50, v51
	v_cvt_pk_bf16_f32 v51, v52, v53
	v_pk_mul_f32 v[52:53], v[58:59], v[146:147]
	v_pk_mul_f32 v[54:55], v[60:61], v[148:149]
	v_addc_co_u32_e32 v33, vcc, 0, v115, vcc
	v_cvt_pk_bf16_f32 v20, v20, v21
	v_cvt_pk_bf16_f32 v21, v22, v23
	v_cvt_pk_bf16_f32 v22, v16, v17
	v_pk_mul_f32 v[16:17], v[18:19], v[148:149]
	s_mov_b32 s4, 0x1400000
	v_cvt_pk_bf16_f32 v52, v52, v53
	v_cvt_pk_bf16_f32 v53, v54, v55
	v_cvt_pk_bf16_f32 v23, v16, v17
	v_add_co_u32_e32 v16, vcc, s4, v114
	v_pk_mul_f32 v[4:5], v[4:5], v[142:143]
	v_pk_mul_f32 v[6:7], v[6:7], v[144:145]
	v_pk_mul_f32 v[0:1], v[0:1], v[146:147]
	global_store_dwordx4 v[56:57], v[50:53], off sc1
	v_addc_co_u32_e32 v17, vcc, 0, v115, vcc
	s_nop 0
	v_pk_mul_f32 v[50:51], v[74:75], v[150:151]
	v_pk_mul_f32 v[52:53], v[76:77], v[152:153]
	v_cvt_pk_bf16_f32 v4, v4, v5
	v_cvt_pk_bf16_f32 v5, v6, v7
	v_cvt_pk_bf16_f32 v6, v0, v1
	v_pk_mul_f32 v[0:1], v[2:3], v[148:149]
	s_mov_b32 s4, 0x1600000
	v_cvt_pk_bf16_f32 v50, v50, v51
	v_cvt_pk_bf16_f32 v51, v52, v53
	v_pk_mul_f32 v[52:53], v[66:67], v[154:155]
	v_pk_mul_f32 v[56:57], v[68:69], v[156:157]
	global_store_dwordx4 v[32:33], v[36:39], off sc1
	v_pk_mul_f32 v[32:33], v[44:45], v[150:151]
	v_pk_mul_f32 v[34:35], v[46:47], v[152:153]
	v_cvt_pk_bf16_f32 v7, v0, v1
	v_add_co_u32_e32 v0, vcc, s4, v114
	v_lshl_add_u64 v[54:55], v[114:115], 0, s[28:29]
	v_cvt_pk_bf16_f32 v52, v52, v53
	v_cvt_pk_bf16_f32 v53, v56, v57
	s_mov_b64 s[28:29], 0x1200000
	v_cvt_pk_bf16_f32 v32, v32, v33
	v_cvt_pk_bf16_f32 v33, v34, v35
	v_pk_mul_f32 v[34:35], v[40:41], v[154:155]
	v_pk_mul_f32 v[36:37], v[42:43], v[156:157]
	global_store_dwordx4 v[16:17], v[20:23], off sc1
	v_pk_mul_f32 v[16:17], v[28:29], v[150:151]
	v_pk_mul_f32 v[18:19], v[30:31], v[152:153]
	v_addc_co_u32_e32 v1, vcc, 0, v115, vcc
	global_store_dwordx4 v[54:55], v[50:53], off offset:256 sc1
	v_cvt_pk_bf16_f32 v34, v34, v35
	v_cvt_pk_bf16_f32 v35, v36, v37
	v_lshl_add_u64 v[50:51], v[114:115], 0, s[28:29]
	s_mov_b64 s[28:29], 0x1400000
	v_cvt_pk_bf16_f32 v16, v16, v17
	v_cvt_pk_bf16_f32 v17, v18, v19
	v_pk_mul_f32 v[18:19], v[24:25], v[154:155]
	v_pk_mul_f32 v[20:21], v[26:27], v[156:157]
	global_store_dwordx4 v[0:1], v[4:7], off sc1
	v_pk_mul_f32 v[0:1], v[8:9], v[150:151]
	v_pk_mul_f32 v[2:3], v[10:11], v[152:153]
	global_store_dwordx4 v[50:51], v[32:35], off offset:256 sc1
	v_cvt_pk_bf16_f32 v18, v18, v19
	v_cvt_pk_bf16_f32 v19, v20, v21
	v_lshl_add_u64 v[32:33], v[114:115], 0, s[28:29]
	s_mov_b64 s[28:29], 0x1600000
	v_cvt_pk_bf16_f32 v0, v0, v1
	v_cvt_pk_bf16_f32 v1, v2, v3
	v_pk_mul_f32 v[2:3], v[12:13], v[154:155]
	v_pk_mul_f32 v[4:5], v[14:15], v[156:157]
	global_store_dwordx4 v[32:33], v[16:19], off offset:256 sc1
	v_cvt_pk_bf16_f32 v2, v2, v3
	v_cvt_pk_bf16_f32 v3, v4, v5
	v_lshl_add_u64 v[16:17], v[114:115], 0, s[28:29]
	s_andn2_b64 vcc, exec, s[6:7]
	s_mov_b64 s[6:7], -1
	global_store_dwordx4 v[16:17], v[0:3], off offset:256 sc1
	s_cbranch_vccnz .LBB0_35
	s_andn2_b64 vcc, exec, s[12:13]
	s_cbranch_vccnz .LBB0_45
	s_lshl_b32 s4, s0, 12
	s_and_b32 s4, s4, 0x1000
	s_add_i32 m0, s44, s4
	s_lshl_b32 s4, s22, 8
	s_add_i32 s6, s4, s45
	s_ashr_i32 s7, s6, 31
	v_lshl_add_u64 v[0:1], s[6:7], 4, v[136:137]
	global_load_lds_dwordx4 v[0:1], off

.LBB0_90:
	s_lshl_b32 s4, s4, 12
	s_and_b32 s4, s4, 0x1000
	v_add_u32_e32 v161, s4, v166
	ds_read_b128 v[168:171], v161
	global_load_dwordx4 v[138:141], v[154:155], off offset:16
	global_load_dwordx4 v[142:145], v[154:155], off
	global_load_dwordx4 v[130:133], v[154:155], off offset:144
	global_load_dwordx4 v[134:137], v[154:155], off offset:128
	v_lshl_add_u32 v160, s33, 8, v163
	s_mov_b64 s[30:31], 0x40000
	s_waitcnt lgkmcnt(0)
	v_add_f32_e32 v168, v168, v169
	v_add_f32_e32 v169, v170, v171
	v_pk_mul_f32 v[170:171], v[114:115], v[114:115]
	v_add_f32_e32 v168, v168, v169
	v_fmamk_f32 v168, v168, 0x3a800000, v191
	v_rsq_f32_e32 v178, v168
	v_pk_mul_f32 v[168:169], v[116:117], v[116:117]
	v_pk_fma_f32 v[170:171], v[118:119], v[118:119], v[170:171]
	v_pk_fma_f32 v[168:169], v[120:121], v[120:121], v[168:169]
	v_pk_fma_f32 v[170:171], v[126:127], v[126:127], v[170:171]
	v_pk_fma_f32 v[168:169], v[128:129], v[128:129], v[168:169]
	v_pk_fma_f32 v[174:175], v[122:123], v[122:123], v[170:171]
	v_pk_fma_f32 v[172:173], v[124:125], v[124:125], v[168:169]
	ds_read_b128 v[168:171], v161 offset:256
	v_pk_mov_b32 v[176:177], v[174:175], v[172:173] op_sel:[1,0]
	v_mov_b32_e32 v175, v173
	v_pk_add_f32 v[172:173], v[176:177], v[174:175]
	s_waitcnt lgkmcnt(0)
	v_add_f32_e32 v168, v168, v169
	v_add_f32_e32 v169, v170, v171
	v_pk_mul_f32 v[170:171], v[98:99], v[98:99]
	v_add_f32_e32 v168, v168, v169
	v_fmamk_f32 v168, v168, 0x3a800000, v191
	v_rsq_f32_e32 v180, v168
	v_pk_mul_f32 v[168:169], v[100:101], v[100:101]
	v_pk_fma_f32 v[170:171], v[102:103], v[102:103], v[170:171]
	v_pk_fma_f32 v[168:169], v[104:105], v[104:105], v[168:169]
	v_pk_fma_f32 v[170:171], v[106:107], v[106:107], v[170:171]
	v_pk_fma_f32 v[168:169], v[108:109], v[108:109], v[168:169]
	v_add_f32_e32 v179, v172, v173
	v_pk_fma_f32 v[172:173], v[112:113], v[112:113], v[168:169]
	v_pk_fma_f32 v[174:175], v[110:111], v[110:111], v[170:171]
	ds_read_b128 v[168:171], v161 offset:512
	v_pk_mov_b32 v[176:177], v[174:175], v[172:173] op_sel:[1,0]
	v_mov_b32_e32 v175, v173
	v_pk_add_f32 v[172:173], v[176:177], v[174:175]
	s_waitcnt lgkmcnt(0)
	v_add_f32_e32 v168, v168, v169
	v_add_f32_e32 v169, v170, v171
	v_pk_mul_f32 v[170:171], v[82:83], v[82:83]
	v_add_f32_e32 v168, v168, v169
	v_fmamk_f32 v168, v168, 0x3a800000, v191
	v_rsq_f32_e32 v182, v168
	v_pk_mul_f32 v[168:169], v[84:85], v[84:85]
	v_pk_fma_f32 v[170:171], v[86:87], v[86:87], v[170:171]
	v_pk_fma_f32 v[168:169], v[88:89], v[88:89], v[168:169]
	v_pk_fma_f32 v[170:171], v[90:91], v[90:91], v[170:171]
	v_pk_fma_f32 v[168:169], v[92:93], v[92:93], v[168:169]
	v_add_f32_e32 v181, v172, v173
	v_pk_fma_f32 v[172:173], v[96:97], v[96:97], v[168:169]
	v_pk_fma_f32 v[174:175], v[94:95], v[94:95], v[170:171]
	ds_read_b128 v[168:171], v161 offset:768
	v_pk_mov_b32 v[176:177], v[174:175], v[172:173] op_sel:[1,0]
	v_mov_b32_e32 v175, v173
	v_pk_add_f32 v[172:173], v[176:177], v[174:175]
	s_waitcnt lgkmcnt(0)
	v_add_f32_e32 v168, v168, v169
	v_add_f32_e32 v169, v170, v171
	v_pk_mul_f32 v[170:171], v[50:51], v[50:51]
	v_add_f32_e32 v168, v168, v169
	v_fmamk_f32 v168, v168, 0x3a800000, v191
	v_rsq_f32_e32 v184, v168
	v_pk_mul_f32 v[168:169], v[52:53], v[52:53]
	v_pk_fma_f32 v[170:171], v[54:55], v[54:55], v[170:171]
	v_pk_fma_f32 v[168:169], v[56:57], v[56:57], v[168:169]
	v_pk_fma_f32 v[170:171], v[74:75], v[74:75], v[170:171]
	v_pk_fma_f32 v[168:169], v[76:77], v[76:77], v[168:169]
	v_add_f32_e32 v183, v172, v173
	v_pk_fma_f32 v[172:173], v[80:81], v[80:81], v[168:169]
	v_pk_fma_f32 v[174:175], v[78:79], v[78:79], v[170:171]
	ds_read_b128 v[168:171], v161 offset:2048
	v_pk_mov_b32 v[176:177], v[174:175], v[172:173] op_sel:[1,0]
	v_mov_b32_e32 v175, v173
	v_pk_add_f32 v[172:173], v[176:177], v[174:175]
	s_waitcnt vmcnt(0)
	v_pk_mul_f32 v[120:121], v[120:121], v[144:145]
	s_waitcnt lgkmcnt(0)
	v_add_f32_e32 v168, v168, v169
	v_add_f32_e32 v169, v170, v171
	v_pk_mul_f32 v[170:171], v[58:59], v[58:59]
	v_add_f32_e32 v168, v168, v169
	v_fmamk_f32 v168, v168, 0x3a800000, v191
	v_rsq_f32_e32 v186, v168
	v_pk_mul_f32 v[168:169], v[60:61], v[60:61]
	v_pk_fma_f32 v[170:171], v[62:63], v[62:63], v[170:171]
	v_pk_fma_f32 v[168:169], v[64:65], v[64:65], v[168:169]
	v_pk_fma_f32 v[170:171], v[66:67], v[66:67], v[170:171]
	v_pk_fma_f32 v[168:169], v[68:69], v[68:69], v[168:169]
	v_add_f32_e32 v185, v172, v173
	v_pk_fma_f32 v[172:173], v[72:73], v[72:73], v[168:169]
	v_pk_fma_f32 v[174:175], v[70:71], v[70:71], v[170:171]
	ds_read_b128 v[168:171], v161 offset:2304
	v_pk_mov_b32 v[176:177], v[174:175], v[172:173] op_sel:[1,0]
	v_mov_b32_e32 v175, v173
	v_pk_add_f32 v[172:173], v[176:177], v[174:175]
	v_pk_mul_f32 v[118:119], v[118:119], v[142:143]
	s_waitcnt lgkmcnt(0)
	v_add_f32_e32 v168, v168, v169
	v_add_f32_e32 v169, v170, v171
	v_pk_mul_f32 v[170:171], v[32:33], v[32:33]
	v_add_f32_e32 v168, v168, v169
	v_fmamk_f32 v168, v168, 0x3a800000, v191
	v_rsq_f32_e32 v188, v168
	v_pk_mul_f32 v[168:169], v[34:35], v[34:35]
	v_pk_fma_f32 v[170:171], v[36:37], v[36:37], v[170:171]
	v_pk_fma_f32 v[168:169], v[38:39], v[38:39], v[168:169]
	v_pk_fma_f32 v[170:171], v[40:41], v[40:41], v[170:171]
	v_pk_fma_f32 v[168:169], v[42:43], v[42:43], v[168:169]
	v_add_f32_e32 v187, v172, v173
	v_pk_fma_f32 v[172:173], v[46:47], v[46:47], v[168:169]
	v_pk_fma_f32 v[174:175], v[44:45], v[44:45], v[170:171]
	ds_read_b128 v[168:171], v161 offset:2560
	v_pk_mov_b32 v[176:177], v[174:175], v[172:173] op_sel:[1,0]
	v_mov_b32_e32 v175, v173
	v_pk_add_f32 v[172:173], v[176:177], v[174:175]
	v_pk_mul_f32 v[114:115], v[114:115], v[138:139]
	s_waitcnt lgkmcnt(0)
	v_add_f32_e32 v168, v168, v169
	v_add_f32_e32 v169, v170, v171
	v_pk_mul_f32 v[170:171], v[16:17], v[16:17]
	v_add_f32_e32 v168, v168, v169
	v_fmamk_f32 v168, v168, 0x3a800000, v191
	v_rsq_f32_e32 v198, v168
	v_pk_mul_f32 v[168:169], v[18:19], v[18:19]
	v_pk_fma_f32 v[170:171], v[20:21], v[20:21], v[170:171]
	v_pk_fma_f32 v[168:169], v[22:23], v[22:23], v[168:169]
	v_pk_fma_f32 v[170:171], v[24:25], v[24:25], v[170:171]
	v_pk_fma_f32 v[168:169], v[26:27], v[26:27], v[168:169]
	v_add_f32_e32 v189, v172, v173
	v_pk_fma_f32 v[172:173], v[30:31], v[30:31], v[168:169]
	v_pk_fma_f32 v[174:175], v[28:29], v[28:29], v[170:171]
	ds_read_b128 v[168:171], v161 offset:2816
	v_pk_mov_b32 v[176:177], v[174:175], v[172:173] op_sel:[1,0]
	v_mov_b32_e32 v175, v173
	v_pk_add_f32 v[172:173], v[176:177], v[174:175]
	v_pk_mul_f32 v[116:117], v[116:117], v[140:141]
	s_waitcnt lgkmcnt(0)
	v_add_f32_e32 v168, v168, v169
	v_add_f32_e32 v169, v170, v171
	v_pk_mul_f32 v[170:171], v[0:1], v[0:1]
	v_add_f32_e32 v168, v168, v169
	v_fmamk_f32 v168, v168, 0x3a800000, v191
	v_rsq_f32_e32 v176, v168
	v_pk_mul_f32 v[168:169], v[2:3], v[2:3]
	v_pk_fma_f32 v[170:171], v[4:5], v[4:5], v[170:171]
	v_pk_fma_f32 v[168:169], v[6:7], v[6:7], v[168:169]
	v_pk_fma_f32 v[170:171], v[8:9], v[8:9], v[170:171]
	v_pk_fma_f32 v[168:169], v[10:11], v[10:11], v[168:169]
	v_pk_fma_f32 v[170:171], v[12:13], v[12:13], v[170:171]
	v_pk_fma_f32 v[168:169], v[14:15], v[14:15], v[168:169]
	v_add_f32_e32 v161, v172, v173
	v_pk_mov_b32 v[172:173], v[170:171], v[168:169] op_sel:[1,0]
	v_mov_b32_e32 v171, v169
	v_pk_add_f32 v[168:169], v[172:173], v[170:171]
	v_and_b32_e32 v170, 64, v228
	v_add_f32_e32 v168, v168, v169
	v_xor_b32_e32 v169, 16, v228
	v_add_u32_e32 v170, 64, v170
	v_cmp_lt_i32_e32 vcc, v169, v170
	v_pk_mul_f32 v[122:123], v[122:123], v[130:131]
	v_pk_mul_f32 v[102:103], v[102:103], v[142:143]
	v_cndmask_b32_e32 v169, v228, v169, vcc
	v_lshlrev_b32_e32 v169, 2, v169
	ds_bpermute_b32 v171, v169, v179
	ds_bpermute_b32 v172, v169, v181
	ds_bpermute_b32 v173, v169, v183
	ds_bpermute_b32 v174, v169, v185
	ds_bpermute_b32 v175, v169, v187
	ds_bpermute_b32 v199, v169, v161
	ds_bpermute_b32 v177, v169, v189
	ds_bpermute_b32 v169, v169, v168
	s_waitcnt lgkmcnt(7)
	v_add_f32_e32 v171, v179, v171
	s_waitcnt lgkmcnt(6)
	v_add_f32_e32 v179, v181, v172
	s_waitcnt lgkmcnt(5)
	v_add_f32_e32 v181, v183, v173
	s_waitcnt lgkmcnt(4)
	v_add_f32_e32 v183, v185, v174
	s_waitcnt lgkmcnt(3)
	v_add_f32_e32 v185, v187, v175
	s_waitcnt lgkmcnt(2)
	v_add_f32_e32 v187, v161, v199
	v_xor_b32_e32 v161, 32, v228
	v_cmp_lt_i32_e32 vcc, v161, v170
	s_waitcnt lgkmcnt(1)
	v_add_f32_e32 v177, v189, v177
	s_waitcnt lgkmcnt(0)
	v_add_f32_e32 v189, v168, v169
	v_cndmask_b32_e32 v161, v228, v161, vcc
	v_lshlrev_b32_e32 v161, 2, v161
	ds_bpermute_b32 v168, v161, v171
	v_mul_f32_e32 v169, v178, v178
	ds_bpermute_b32 v199, v161, v179
	ds_bpermute_b32 v200, v161, v181
	ds_bpermute_b32 v201, v161, v183
	s_waitcnt lgkmcnt(3)
	v_add_f32_e32 v168, v171, v168
	v_mul_f32_e32 v168, v169, v168
	v_fmamk_f32 v168, v168, 0x3c800000, v191
	v_rsq_f32_e32 v170, v168
	ds_bpermute_b32 v171, v161, v189
	ds_bpermute_b32 v202, v161, v185
	ds_bpermute_b32 v203, v161, v177
	ds_bpermute_b32 v204, v161, v187
	v_mul_f32_e32 v161, v178, v170
	v_lshl_or_b32 v168, s0, 8, v165
	v_mul_f32_e32 v170, v162, v161
	v_ashrrev_i32_e32 v161, 31, v160
	v_ashrrev_i32_e32 v169, 31, v168
	v_lshlrev_b64 v[172:173], 11, v[160:161]
	s_waitcnt lgkmcnt(3)
	v_pk_mul_f32 v[120:121], v[120:121], v[170:171] op_sel_hi:[1,0]
	v_pk_mul_f32 v[118:119], v[118:119], v[170:171] op_sel_hi:[1,0]
	v_pk_mul_f32 v[114:115], v[114:115], v[170:171] op_sel_hi:[1,0]
	v_pk_mul_f32 v[174:175], v[116:117], v[170:171] op_sel_hi:[1,0]
	v_cvt_pk_bf16_f32 v116, v118, v119
	v_cvt_pk_bf16_f32 v117, v120, v121
	v_cvt_pk_bf16_f32 v118, v114, v115
	v_lshl_add_u64 v[114:115], s[18:19], 0, v[172:173]
	v_lshlrev_b64 v[120:121], 1, v[168:169]
	v_cvt_pk_bf16_f32 v119, v174, v175
	v_lshl_add_u64 v[114:115], v[114:115], 0, v[120:121]
	global_store_dwordx4 v[114:115], v[116:119], off sc1
	v_pk_mul_f32 v[104:105], v[104:105], v[144:145]
	v_pk_mul_f32 v[100:101], v[100:101], v[140:141]
	v_pk_mul_f32 v[116:117], v[128:129], v[136:137]
	v_pk_mul_f32 v[118:119], v[126:127], v[134:135]
	v_pk_mul_f32 v[126:127], v[116:117], v[170:171] op_sel_hi:[1,0]
	v_pk_mul_f32 v[116:117], v[118:119], v[170:171] op_sel_hi:[1,0]
	v_pk_mul_f32 v[118:119], v[124:125], v[132:133]
	v_cvt_pk_bf16_f32 v116, v116, v117
	v_pk_mul_f32 v[124:125], v[118:119], v[170:171] op_sel_hi:[1,0]
	v_pk_mul_f32 v[118:119], v[122:123], v[170:171] op_sel_hi:[1,0]
	v_mul_f32_e32 v122, v180, v180
	v_cvt_pk_bf16_f32 v118, v118, v119
	v_add_f32_e32 v119, v179, v199
	v_mul_f32_e32 v119, v122, v119
	v_fmamk_f32 v119, v119, 0x3c800000, v191
	v_rsq_f32_e32 v122, v119
	v_cvt_pk_bf16_f32 v117, v126, v127
	v_cvt_pk_bf16_f32 v119, v124, v125
	global_store_dwordx4 v[114:115], v[116:119], off offset:64 sc1
	v_pk_mul_f32 v[98:99], v[98:99], v[138:139]
	v_pk_mul_f32 v[86:87], v[86:87], v[142:143]
	v_or_b32_e32 v116, 16, v160
	v_mul_f32_e32 v117, v180, v122
	v_mul_f32_e32 v118, v162, v117
	v_ashrrev_i32_e32 v117, 31, v116
	v_lshlrev_b64 v[116:117], 11, v[116:117]
	v_pk_mul_f32 v[102:103], v[102:103], v[118:119] op_sel_hi:[1,0]
	v_pk_mul_f32 v[104:105], v[104:105], v[118:119] op_sel_hi:[1,0]
	v_pk_mul_f32 v[122:123], v[100:101], v[118:119] op_sel_hi:[1,0]
	v_pk_mul_f32 v[100:101], v[98:99], v[118:119] op_sel_hi:[1,0]
	v_cvt_pk_bf16_f32 v98, v102, v103
	v_lshl_add_u64 v[102:103], s[18:19], 0, v[116:117]
	v_cvt_pk_bf16_f32 v99, v104, v105
	v_cvt_pk_bf16_f32 v100, v100, v101
	v_cvt_pk_bf16_f32 v101, v122, v123
	v_lshl_add_u64 v[102:103], v[102:103], 0, v[120:121]
	global_store_dwordx4 v[102:103], v[98:101], off sc1
	v_pk_mul_f32 v[88:89], v[88:89], v[144:145]
	v_pk_mul_f32 v[84:85], v[84:85], v[140:141]
	v_pk_mul_f32 v[98:99], v[108:109], v[136:137]
	v_pk_mul_f32 v[100:101], v[106:107], v[134:135]
	v_pk_mul_f32 v[104:105], v[98:99], v[118:119] op_sel_hi:[1,0]
	v_pk_mul_f32 v[98:99], v[100:101], v[118:119] op_sel_hi:[1,0]
	v_pk_mul_f32 v[100:101], v[112:113], v[132:133]
	v_pk_mul_f32 v[106:107], v[110:111], v[130:131]
	v_pk_mul_f32 v[108:109], v[100:101], v[118:119] op_sel_hi:[1,0]
	v_pk_mul_f32 v[100:101], v[106:107], v[118:119] op_sel_hi:[1,0]
	v_cvt_pk_bf16_f32 v98, v98, v99
	v_cvt_pk_bf16_f32 v99, v104, v105
	v_cvt_pk_bf16_f32 v100, v100, v101
	v_add_f32_e32 v101, v181, v200
	v_mul_f32_e32 v104, v182, v182
	v_mul_f32_e32 v101, v104, v101
	v_fmamk_f32 v101, v101, 0x3c800000, v191
	v_rsq_f32_e32 v104, v101
	v_cvt_pk_bf16_f32 v101, v108, v109
	global_store_dwordx4 v[102:103], v[98:101], off offset:64 sc1
	v_pk_mul_f32 v[82:83], v[82:83], v[138:139]
	v_pk_mul_f32 v[54:55], v[54:55], v[142:143]
	v_or_b32_e32 v98, 32, v160
	v_mul_f32_e32 v99, v182, v104
	v_mul_f32_e32 v100, v162, v99
	v_ashrrev_i32_e32 v99, 31, v98
	v_lshlrev_b64 v[98:99], 11, v[98:99]
	v_pk_mul_f32 v[86:87], v[86:87], v[100:101] op_sel_hi:[1,0]
	v_pk_mul_f32 v[88:89], v[88:89], v[100:101] op_sel_hi:[1,0]
	v_pk_mul_f32 v[102:103], v[84:85], v[100:101] op_sel_hi:[1,0]
	v_pk_mul_f32 v[84:85], v[82:83], v[100:101] op_sel_hi:[1,0]
	v_cvt_pk_bf16_f32 v82, v86, v87
	v_lshl_add_u64 v[86:87], s[18:19], 0, v[98:99]
	v_cvt_pk_bf16_f32 v83, v88, v89
	v_cvt_pk_bf16_f32 v84, v84, v85
	v_cvt_pk_bf16_f32 v85, v102, v103
	v_lshl_add_u64 v[86:87], v[86:87], 0, v[120:121]
	global_store_dwordx4 v[86:87], v[82:85], off sc1
	v_pk_mul_f32 v[56:57], v[56:57], v[144:145]
	v_pk_mul_f32 v[52:53], v[52:53], v[140:141]
	v_pk_mul_f32 v[82:83], v[92:93], v[136:137]
	v_pk_mul_f32 v[84:85], v[90:91], v[134:135]
	v_pk_mul_f32 v[88:89], v[82:83], v[100:101] op_sel_hi:[1,0]
	v_pk_mul_f32 v[82:83], v[84:85], v[100:101] op_sel_hi:[1,0]
	v_pk_mul_f32 v[84:85], v[96:97], v[132:133]
	v_pk_mul_f32 v[90:91], v[94:95], v[130:131]
	v_pk_mul_f32 v[92:93], v[84:85], v[100:101] op_sel_hi:[1,0]
	v_pk_mul_f32 v[84:85], v[90:91], v[100:101] op_sel_hi:[1,0]
	v_cvt_pk_bf16_f32 v82, v82, v83
	v_cvt_pk_bf16_f32 v83, v88, v89
	v_cvt_pk_bf16_f32 v84, v84, v85
	v_add_f32_e32 v85, v183, v201
	v_mul_f32_e32 v88, v184, v184
	v_mul_f32_e32 v85, v88, v85
	v_fmamk_f32 v85, v85, 0x3c800000, v191
	v_rsq_f32_e32 v88, v85
	v_cvt_pk_bf16_f32 v85, v92, v93
	global_store_dwordx4 v[86:87], v[82:85], off offset:64 sc1
	v_pk_mul_f32 v[50:51], v[50:51], v[138:139]
	v_pk_mul_f32 v[58:59], v[58:59], v[138:139]
	v_or_b32_e32 v82, 48, v160
	v_mul_f32_e32 v83, v184, v88
	v_mul_f32_e32 v84, v162, v83
	v_ashrrev_i32_e32 v83, 31, v82
	v_lshlrev_b64 v[82:83], 11, v[82:83]
	v_pk_mul_f32 v[54:55], v[54:55], v[84:85] op_sel_hi:[1,0]
	v_pk_mul_f32 v[56:57], v[56:57], v[84:85] op_sel_hi:[1,0]
	v_pk_mul_f32 v[86:87], v[52:53], v[84:85] op_sel_hi:[1,0]
	v_pk_mul_f32 v[52:53], v[50:51], v[84:85] op_sel_hi:[1,0]
	v_cvt_pk_bf16_f32 v50, v54, v55
	v_lshl_add_u64 v[54:55], s[18:19], 0, v[82:83]
	v_cvt_pk_bf16_f32 v51, v56, v57
	v_cvt_pk_bf16_f32 v52, v52, v53
	v_cvt_pk_bf16_f32 v53, v86, v87
	v_lshl_add_u64 v[54:55], v[54:55], 0, v[120:121]
	global_store_dwordx4 v[54:55], v[50:53], off sc1
	v_pk_mul_f32 v[38:39], v[38:39], v[144:145]
	v_pk_mul_f32 v[36:37], v[36:37], v[142:143]
	v_pk_mul_f32 v[50:51], v[76:77], v[136:137]
	v_pk_mul_f32 v[52:53], v[74:75], v[134:135]
	v_pk_mul_f32 v[56:57], v[50:51], v[84:85] op_sel_hi:[1,0]
	v_pk_mul_f32 v[50:51], v[52:53], v[84:85] op_sel_hi:[1,0]
	v_pk_mul_f32 v[52:53], v[80:81], v[132:133]
	v_cvt_pk_bf16_f32 v50, v50, v51
	v_cvt_pk_bf16_f32 v51, v56, v57
	s_waitcnt lgkmcnt(2)
	v_add_f32_e32 v56, v185, v202
	v_mul_f32_e32 v57, v186, v186
	v_mul_f32_e32 v56, v57, v56
	v_fmamk_f32 v56, v56, 0x3c800000, v191
	v_rsq_f32_e32 v56, v56
	v_pk_mul_f32 v[74:75], v[78:79], v[130:131]
	v_pk_mul_f32 v[76:77], v[52:53], v[84:85] op_sel_hi:[1,0]
	v_pk_mul_f32 v[52:53], v[74:75], v[84:85] op_sel_hi:[1,0]
	v_pk_mul_f32 v[34:35], v[34:35], v[140:141]
	v_cvt_pk_bf16_f32 v52, v52, v53
	v_cvt_pk_bf16_f32 v53, v76, v77
	global_store_dwordx4 v[54:55], v[50:53], off offset:64 sc1
	v_pk_mul_f32 v[32:33], v[32:33], v[138:139]
	v_pk_mul_f32 v[22:23], v[22:23], v[144:145]
	v_mul_f32_e32 v50, v186, v56
	v_mul_f32_e32 v54, v162, v50
	v_pk_mul_f32 v[50:51], v[64:65], v[144:145]
	v_pk_mul_f32 v[52:53], v[62:63], v[142:143]
	v_pk_mul_f32 v[56:57], v[50:51], v[54:55] op_sel_hi:[1,0]
	v_pk_mul_f32 v[50:51], v[52:53], v[54:55] op_sel_hi:[1,0]
	v_pk_mul_f32 v[52:53], v[60:61], v[140:141]
	v_cvt_pk_bf16_f32 v50, v50, v51
	v_pk_mul_f32 v[60:61], v[52:53], v[54:55] op_sel_hi:[1,0]
	v_pk_mul_f32 v[52:53], v[58:59], v[54:55] op_sel_hi:[1,0]
	v_add_co_u32_e32 v58, vcc, s63, v114
	v_cvt_pk_bf16_f32 v51, v56, v57
	v_cvt_pk_bf16_f32 v52, v52, v53
	v_cvt_pk_bf16_f32 v53, v60, v61
	v_addc_co_u32_e32 v59, vcc, 0, v115, vcc
	global_store_dwordx4 v[58:59], v[50:53], off sc1
	v_pk_mul_f32 v[60:61], v[70:71], v[130:131]
	v_lshl_add_u64 v[56:57], v[114:115], 0, s[30:31]
	v_pk_mul_f32 v[50:51], v[68:69], v[136:137]
	v_pk_mul_f32 v[52:53], v[66:67], v[134:135]
	v_pk_mul_f32 v[58:59], v[50:51], v[54:55] op_sel_hi:[1,0]
	v_pk_mul_f32 v[50:51], v[52:53], v[54:55] op_sel_hi:[1,0]
	v_pk_mul_f32 v[52:53], v[72:73], v[132:133]
	v_cvt_pk_bf16_f32 v50, v50, v51
	v_pk_mul_f32 v[62:63], v[52:53], v[54:55] op_sel_hi:[1,0]
	v_pk_mul_f32 v[52:53], v[60:61], v[54:55] op_sel_hi:[1,0]
	s_waitcnt lgkmcnt(1)
	v_add_f32_e32 v54, v177, v203
	v_mul_f32_e32 v55, v188, v188
	v_mul_f32_e32 v54, v55, v54
	v_fmamk_f32 v54, v54, 0x3c800000, v191
	v_rsq_f32_e32 v54, v54
	v_cvt_pk_bf16_f32 v51, v58, v59
	v_cvt_pk_bf16_f32 v52, v52, v53
	v_cvt_pk_bf16_f32 v53, v62, v63
	global_store_dwordx4 v[56:57], v[50:53], off offset:64 sc1
	s_mov_b64 s[30:31], 0x48000
	v_pk_mul_f32 v[20:21], v[20:21], v[142:143]
	v_mul_f32_e32 v50, v188, v54
	v_mul_f32_e32 v50, v162, v50
	v_pk_mul_f32 v[38:39], v[38:39], v[50:51] op_sel_hi:[1,0]
	v_pk_mul_f32 v[36:37], v[36:37], v[50:51] op_sel_hi:[1,0]
	v_pk_mul_f32 v[52:53], v[34:35], v[50:51] op_sel_hi:[1,0]
	v_pk_mul_f32 v[34:35], v[32:33], v[50:51] op_sel_hi:[1,0]
	v_cvt_pk_bf16_f32 v33, v38, v39
	v_add_co_u32_e32 v38, vcc, s64, v114
	v_cvt_pk_bf16_f32 v32, v36, v37
	v_cvt_pk_bf16_f32 v34, v34, v35
	v_cvt_pk_bf16_f32 v35, v52, v53
	v_addc_co_u32_e32 v39, vcc, 0, v115, vcc
	global_store_dwordx4 v[38:39], v[32:35], off sc1
	v_lshl_add_u64 v[36:37], v[114:115], 0, s[30:31]
	v_pk_mul_f32 v[18:19], v[18:19], v[140:141]
	v_pk_mul_f32 v[32:33], v[42:43], v[136:137]
	v_pk_mul_f32 v[34:35], v[40:41], v[134:135]
	v_pk_mul_f32 v[38:39], v[32:33], v[50:51] op_sel_hi:[1,0]
	v_pk_mul_f32 v[32:33], v[34:35], v[50:51] op_sel_hi:[1,0]
	v_pk_mul_f32 v[34:35], v[46:47], v[132:133]
	v_cvt_pk_bf16_f32 v32, v32, v33
	v_cvt_pk_bf16_f32 v33, v38, v39
	s_waitcnt lgkmcnt(0)
	v_add_f32_e32 v38, v187, v204
	v_mul_f32_e32 v39, v198, v198
	v_mul_f32_e32 v38, v39, v38
	v_fmamk_f32 v38, v38, 0x3c800000, v191
	v_rsq_f32_e32 v38, v38
	v_pk_mul_f32 v[40:41], v[44:45], v[130:131]
	v_pk_mul_f32 v[42:43], v[34:35], v[50:51] op_sel_hi:[1,0]
	v_pk_mul_f32 v[34:35], v[40:41], v[50:51] op_sel_hi:[1,0]
	v_pk_mul_f32 v[16:17], v[16:17], v[138:139]
	v_cvt_pk_bf16_f32 v34, v34, v35
	v_cvt_pk_bf16_f32 v35, v42, v43
	global_store_dwordx4 v[36:37], v[32:35], off offset:64 sc1
	s_mov_b64 s[30:31], 0x50000
	v_pk_mul_f32 v[6:7], v[6:7], v[144:145]
	v_mul_f32_e32 v32, v198, v38
	v_mul_f32_e32 v32, v162, v32
	v_pk_mul_f32 v[22:23], v[22:23], v[32:33] op_sel_hi:[1,0]
	v_pk_mul_f32 v[20:21], v[20:21], v[32:33] op_sel_hi:[1,0]
	v_pk_mul_f32 v[34:35], v[18:19], v[32:33] op_sel_hi:[1,0]
	v_pk_mul_f32 v[18:19], v[16:17], v[32:33] op_sel_hi:[1,0]
	v_cvt_pk_bf16_f32 v17, v22, v23
	v_add_co_u32_e32 v22, vcc, s67, v114
	v_cvt_pk_bf16_f32 v16, v20, v21
	v_cvt_pk_bf16_f32 v18, v18, v19
	v_cvt_pk_bf16_f32 v19, v34, v35
	v_addc_co_u32_e32 v23, vcc, 0, v115, vcc
	global_store_dwordx4 v[22:23], v[16:19], off sc1
	v_lshl_add_u64 v[20:21], v[114:115], 0, s[30:31]
	v_pk_mul_f32 v[4:5], v[4:5], v[142:143]
	v_pk_mul_f32 v[16:17], v[26:27], v[136:137]
	v_pk_mul_f32 v[18:19], v[24:25], v[134:135]
	v_pk_mul_f32 v[22:23], v[16:17], v[32:33] op_sel_hi:[1,0]
	v_pk_mul_f32 v[16:17], v[18:19], v[32:33] op_sel_hi:[1,0]
	v_pk_mul_f32 v[18:19], v[30:31], v[132:133]
	v_cvt_pk_bf16_f32 v16, v16, v17
	v_cvt_pk_bf16_f32 v17, v22, v23
	v_add_f32_e32 v22, v189, v171
	v_mul_f32_e32 v23, v176, v176
	v_mul_f32_e32 v22, v23, v22
	v_fmamk_f32 v22, v22, 0x3c800000, v191
	v_rsq_f32_e32 v22, v22
	v_pk_mul_f32 v[24:25], v[28:29], v[130:131]
	v_pk_mul_f32 v[26:27], v[18:19], v[32:33] op_sel_hi:[1,0]
	v_pk_mul_f32 v[18:19], v[24:25], v[32:33] op_sel_hi:[1,0]
	v_pk_mul_f32 v[2:3], v[2:3], v[140:141]
	v_cvt_pk_bf16_f32 v18, v18, v19
	v_cvt_pk_bf16_f32 v19, v26, v27
	global_store_dwordx4 v[20:21], v[16:19], off offset:64 sc1
	v_pk_mul_f32 v[0:1], v[0:1], v[138:139]
	s_mov_b32 s0, 0x58000
	v_mul_f32_e32 v16, v176, v22
	v_mul_f32_e32 v16, v162, v16
	v_pk_mul_f32 v[6:7], v[6:7], v[16:17] op_sel_hi:[1,0]
	v_pk_mul_f32 v[4:5], v[4:5], v[16:17] op_sel_hi:[1,0]
	v_pk_mul_f32 v[18:19], v[2:3], v[16:17] op_sel_hi:[1,0]
	v_pk_mul_f32 v[2:3], v[0:1], v[16:17] op_sel_hi:[1,0]
	v_cvt_pk_bf16_f32 v1, v6, v7
	v_add_co_u32_e32 v6, vcc, s0, v114
	v_cvt_pk_bf16_f32 v0, v4, v5
	v_cvt_pk_bf16_f32 v2, v2, v3
	v_cvt_pk_bf16_f32 v3, v18, v19
	v_addc_co_u32_e32 v7, vcc, 0, v115, vcc
	global_store_dwordx4 v[6:7], v[0:3], off sc1
	s_mov_b64 s[30:31], 0x58000
	v_lshl_add_u64 v[4:5], v[114:115], 0, s[30:31]
	v_pk_mul_f32 v[0:1], v[10:11], v[136:137]
	v_pk_mul_f32 v[2:3], v[8:9], v[134:135]
	v_pk_mul_f32 v[6:7], v[0:1], v[16:17] op_sel_hi:[1,0]
	v_pk_mul_f32 v[0:1], v[2:3], v[16:17] op_sel_hi:[1,0]
	v_pk_mul_f32 v[2:3], v[14:15], v[132:133]
	v_pk_mul_f32 v[8:9], v[12:13], v[130:131]
	v_pk_mul_f32 v[10:11], v[2:3], v[16:17] op_sel_hi:[1,0]
	v_pk_mul_f32 v[2:3], v[8:9], v[16:17] op_sel_hi:[1,0]
	v_cvt_pk_bf16_f32 v0, v0, v1
	v_cvt_pk_bf16_f32 v1, v6, v7
	v_cvt_pk_bf16_f32 v2, v2, v3
	v_cvt_pk_bf16_f32 v3, v10, v11
	s_andn2_b64 vcc, exec, s[8:9]
	s_mov_b64 s[8:9], -1
	global_store_dwordx4 v[4:5], v[0:3], off offset:64 sc1
	s_cbranch_vccnz .LBB0_83
	s_andn2_b64 vcc, exec, s[14:15]
	s_cbranch_vccnz .LBB0_93
	s_lshl_b32 s0, s22, 8
	s_add_i32 s8, s0, s89
	s_lshl_b32 s0, s1, 12
	s_ashr_i32 s9, s8, 31
	s_and_b32 s0, s0, 0x1000
	v_lshl_add_u64 v[0:1], s[8:9], 4, v[152:153]
	s_add_i32 m0, s88, s0
	s_nop 0
	global_load_lds_dwordx4 v[0:1], off

.LBB0_161:
	s_lshl_b32 s1, s1, 12
	s_and_b32 s1, s1, 0x1000
	v_add_u32_e32 v126, s1, v169
	ds_read_b128 v[172:175], v126
	ds_read_b128 v[176:179], v126 offset:256
	ds_read_b128 v[150:153], v126 offset:512
	ds_read_b128 v[146:149], v126 offset:768
	ds_read_b128 v[142:145], v126 offset:2048
	ds_read_b128 v[138:141], v126 offset:2304
	ds_read_b128 v[134:137], v126 offset:2560
	ds_read_b128 v[126:129], v126 offset:2816
	s_waitcnt lgkmcnt(0)
	v_add_f32_e32 v172, v172, v173
	v_add_f32_e32 v173, v174, v175
	v_pk_mul_f32 v[120:121], v[116:117], v[120:121]
	v_add_f32_e32 v172, v172, v173
	v_fmamk_f32 v172, v172, 0x3a800000, v191
	v_rsq_f32_e32 v173, v172
	v_pk_mul_f32 v[132:133], v[124:125], v[132:133]
	v_lshl_or_b32 v180, s0, 7, v168
	v_lshl_add_u32 v171, s4, 8, v166
	v_mul_f32_e32 v172, 0xbfb8aa3b, v173
	v_mul_f32_e32 v173, v173, v173
	v_pk_mul_f32 v[182:183], v[122:123], v[172:173] op_sel_hi:[1,0]
	v_pk_mul_f32 v[122:123], v[122:123], v[130:131]
	v_pk_mul_f32 v[130:131], v[114:115], v[172:173] op_sel_hi:[1,0]
	v_rcp_f32_e32 v174, v173
	v_exp_f32_e32 v130, v130
	v_exp_f32_e32 v131, v131
	v_pk_mul_f32 v[116:117], v[116:117], v[172:173] op_sel_hi:[1,0]
	v_exp_f32_e32 v182, v182
	v_exp_f32_e32 v183, v183
	v_pk_mul_f32 v[124:125], v[124:125], v[172:173] op_sel_hi:[1,0]
	v_exp_f32_e32 v116, v116
	v_exp_f32_e32 v117, v117
	v_exp_f32_e32 v124, v124
	v_exp_f32_e32 v125, v125
	v_pk_fma_f32 v[130:131], v[174:175], v[130:131], v[174:175] op_sel_hi:[0,1,0]
	v_pk_fma_f32 v[182:183], v[174:175], v[182:183], v[174:175] op_sel_hi:[0,1,0]
	v_rcp_f32_e32 v130, v130
	v_rcp_f32_e32 v131, v131
	v_pk_fma_f32 v[116:117], v[174:175], v[116:117], v[174:175] op_sel_hi:[0,1,0]
	v_rcp_f32_e32 v182, v182
	v_rcp_f32_e32 v183, v183
	v_pk_fma_f32 v[124:125], v[174:175], v[124:125], v[174:175] op_sel_hi:[0,1,0]
	v_rcp_f32_e32 v116, v116
	v_rcp_f32_e32 v117, v117
	v_rcp_f32_e32 v124, v124
	v_rcp_f32_e32 v125, v125
	v_pk_mul_f32 v[114:115], v[114:115], v[118:119]
	v_ashrrev_i32_e32 v181, 31, v180
	v_pk_mul_f32 v[114:115], v[114:115], v[130:131]
	v_pk_mul_f32 v[122:123], v[122:123], v[182:183]
	v_pk_mul_f32 v[116:117], v[120:121], v[116:117]
	v_cvt_pk_bf16_f32 v120, v114, v115
	v_mov_b64_e32 v[114:115], s[16:17]
	v_pk_mul_f32 v[124:125], v[132:133], v[124:125]
	v_cvt_pk_bf16_f32 v118, v122, v123
	v_cvt_pk_bf16_f32 v121, v116, v117
	v_mad_i64_i32 v[122:123], s[0:1], v171, s61, v[114:115]
	v_lshlrev_b64 v[116:117], 1, v[180:181]
	v_cvt_pk_bf16_f32 v119, v124, v125
	v_lshl_add_u64 v[122:123], v[122:123], 0, v[116:117]
	global_store_dwordx4 v[122:123], v[118:121], off sc1
	v_pk_mul_f32 v[112:113], v[108:109], v[112:113]
	v_pk_mul_f32 v[104:105], v[100:101], v[104:105]
	v_add_f32_e32 v118, v176, v177
	v_add_f32_e32 v119, v178, v179
	v_pk_mul_f32 v[96:97], v[92:93], v[96:97]
	v_add_f32_e32 v118, v118, v119
	v_fmamk_f32 v118, v118, 0x3a800000, v191
	v_rsq_f32_e32 v119, v118
	v_pk_mul_f32 v[88:89], v[84:85], v[88:89]
	v_pk_mul_f32 v[80:81], v[76:77], v[80:81]
	v_pk_mul_f32 v[72:73], v[68:69], v[72:73]
	v_mul_f32_e32 v118, 0xbfb8aa3b, v119
	v_mul_f32_e32 v119, v119, v119
	v_pk_mul_f32 v[122:123], v[106:107], v[118:119] op_sel_hi:[1,0]
	v_pk_mul_f32 v[106:107], v[106:107], v[110:111]
	v_pk_mul_f32 v[110:111], v[98:99], v[118:119] op_sel_hi:[1,0]
	v_rcp_f32_e32 v120, v119
	v_exp_f32_e32 v110, v110
	v_exp_f32_e32 v111, v111
	v_pk_mul_f32 v[98:99], v[98:99], v[102:103]
	v_pk_mul_f32 v[108:109], v[108:109], v[118:119] op_sel_hi:[1,0]
	v_exp_f32_e32 v122, v122
	v_pk_fma_f32 v[110:111], v[120:121], v[110:111], v[120:121] op_sel_hi:[0,1,0]
	v_rcp_f32_e32 v110, v110
	v_rcp_f32_e32 v111, v111
	v_exp_f32_e32 v123, v123
	v_exp_f32_e32 v108, v108
	v_exp_f32_e32 v109, v109
	v_pk_mul_f32 v[102:103], v[98:99], v[110:111]
	v_pk_mul_f32 v[98:99], v[100:101], v[118:119] op_sel_hi:[1,0]
	v_pk_fma_f32 v[122:123], v[120:121], v[122:123], v[120:121] op_sel_hi:[0,1,0]
	v_exp_f32_e32 v98, v98
	v_exp_f32_e32 v99, v99
	v_pk_fma_f32 v[108:109], v[120:121], v[108:109], v[120:121] op_sel_hi:[0,1,0]
	v_rcp_f32_e32 v122, v122
	v_rcp_f32_e32 v123, v123
	v_pk_fma_f32 v[98:99], v[120:121], v[98:99], v[120:121] op_sel_hi:[0,1,0]
	v_rcp_f32_e32 v108, v108
	v_rcp_f32_e32 v109, v109
	v_rcp_f32_e32 v98, v98
	v_rcp_f32_e32 v99, v99
	v_or_b32_e32 v110, 16, v171
	v_pk_mul_f32 v[106:107], v[106:107], v[122:123]
	v_pk_mul_f32 v[108:109], v[112:113], v[108:109]
	v_pk_mul_f32 v[104:105], v[104:105], v[98:99]
	v_cvt_pk_bf16_f32 v100, v102, v103
	v_mad_i64_i32 v[102:103], s[0:1], v110, s61, v[114:115]
	v_cvt_pk_bf16_f32 v98, v106, v107
	v_cvt_pk_bf16_f32 v99, v108, v109
	v_cvt_pk_bf16_f32 v101, v104, v105
	v_lshl_add_u64 v[102:103], v[102:103], 0, v[116:117]
	global_store_dwordx4 v[102:103], v[98:101], off sc1
	v_pk_mul_f32 v[64:65], v[60:61], v[64:65]
	v_pk_mul_f32 v[56:57], v[52:53], v[56:57]
	v_add_f32_e32 v98, v150, v151
	v_add_f32_e32 v99, v152, v153
	v_pk_mul_f32 v[46:47], v[42:43], v[46:47]
	v_add_f32_e32 v98, v98, v99
	v_fmamk_f32 v98, v98, 0x3a800000, v191
	v_rsq_f32_e32 v99, v98
	v_pk_mul_f32 v[38:39], v[34:35], v[38:39]
	v_pk_mul_f32 v[30:31], v[26:27], v[30:31]
	v_pk_mul_f32 v[22:23], v[18:19], v[22:23]
	v_mul_f32_e32 v98, 0xbfb8aa3b, v99
	v_mul_f32_e32 v99, v99, v99
	v_pk_mul_f32 v[102:103], v[90:91], v[98:99] op_sel_hi:[1,0]
	v_pk_mul_f32 v[90:91], v[90:91], v[94:95]
	v_pk_mul_f32 v[94:95], v[82:83], v[98:99] op_sel_hi:[1,0]
	v_rcp_f32_e32 v100, v99
	v_exp_f32_e32 v94, v94
	v_exp_f32_e32 v95, v95
	v_pk_mul_f32 v[82:83], v[82:83], v[86:87]
	v_pk_mul_f32 v[92:93], v[92:93], v[98:99] op_sel_hi:[1,0]
	v_exp_f32_e32 v102, v102
	v_pk_fma_f32 v[94:95], v[100:101], v[94:95], v[100:101] op_sel_hi:[0,1,0]
	v_rcp_f32_e32 v94, v94
	v_rcp_f32_e32 v95, v95
	v_exp_f32_e32 v103, v103
	v_exp_f32_e32 v92, v92
	v_exp_f32_e32 v93, v93
	v_pk_mul_f32 v[86:87], v[82:83], v[94:95]
	v_pk_mul_f32 v[82:83], v[84:85], v[98:99] op_sel_hi:[1,0]
	v_pk_fma_f32 v[102:103], v[100:101], v[102:103], v[100:101] op_sel_hi:[0,1,0]
	v_exp_f32_e32 v82, v82
	v_exp_f32_e32 v83, v83
	v_pk_fma_f32 v[92:93], v[100:101], v[92:93], v[100:101] op_sel_hi:[0,1,0]
	v_rcp_f32_e32 v102, v102
	v_rcp_f32_e32 v103, v103
	v_pk_fma_f32 v[82:83], v[100:101], v[82:83], v[100:101] op_sel_hi:[0,1,0]
	v_rcp_f32_e32 v92, v92
	v_rcp_f32_e32 v93, v93
	v_rcp_f32_e32 v82, v82
	v_rcp_f32_e32 v83, v83
	v_or_b32_e32 v94, 32, v171
	v_pk_mul_f32 v[90:91], v[90:91], v[102:103]
	v_pk_mul_f32 v[92:93], v[96:97], v[92:93]
	v_pk_mul_f32 v[88:89], v[88:89], v[82:83]
	v_cvt_pk_bf16_f32 v84, v86, v87
	v_mad_i64_i32 v[86:87], s[0:1], v94, s61, v[114:115]
	v_cvt_pk_bf16_f32 v82, v90, v91
	v_cvt_pk_bf16_f32 v83, v92, v93
	v_cvt_pk_bf16_f32 v85, v88, v89
	v_lshl_add_u64 v[86:87], v[86:87], 0, v[116:117]
	global_store_dwordx4 v[86:87], v[82:85], off sc1
	v_pk_mul_f32 v[14:15], v[10:11], v[14:15]
	v_pk_mul_f32 v[6:7], v[2:3], v[6:7]
	v_add_f32_e32 v82, v146, v147
	v_add_f32_e32 v83, v148, v149
	s_mov_b64 s[28:29], -1
	v_add_f32_e32 v82, v82, v83
	v_fmamk_f32 v82, v82, 0x3a800000, v191
	v_rsq_f32_e32 v83, v82
	s_andn2_b64 vcc, exec, s[8:9]
	v_mul_f32_e32 v82, 0xbfb8aa3b, v83
	v_mul_f32_e32 v83, v83, v83
	v_pk_mul_f32 v[86:87], v[74:75], v[82:83] op_sel_hi:[1,0]
	v_pk_mul_f32 v[74:75], v[74:75], v[78:79]
	v_pk_mul_f32 v[78:79], v[66:67], v[82:83] op_sel_hi:[1,0]
	v_rcp_f32_e32 v84, v83
	v_exp_f32_e32 v78, v78
	v_exp_f32_e32 v79, v79
	v_pk_mul_f32 v[66:67], v[66:67], v[70:71]
	v_pk_mul_f32 v[76:77], v[76:77], v[82:83] op_sel_hi:[1,0]
	v_exp_f32_e32 v86, v86
	v_pk_fma_f32 v[78:79], v[84:85], v[78:79], v[84:85] op_sel_hi:[0,1,0]
	v_rcp_f32_e32 v78, v78
	v_rcp_f32_e32 v79, v79
	v_exp_f32_e32 v87, v87
	v_exp_f32_e32 v76, v76
	v_exp_f32_e32 v77, v77
	v_pk_mul_f32 v[70:71], v[66:67], v[78:79]
	v_pk_mul_f32 v[66:67], v[68:69], v[82:83] op_sel_hi:[1,0]
	v_pk_fma_f32 v[86:87], v[84:85], v[86:87], v[84:85] op_sel_hi:[0,1,0]
	v_exp_f32_e32 v66, v66
	v_exp_f32_e32 v67, v67
	v_pk_fma_f32 v[76:77], v[84:85], v[76:77], v[84:85] op_sel_hi:[0,1,0]
	v_rcp_f32_e32 v86, v86
	v_rcp_f32_e32 v87, v87
	v_pk_fma_f32 v[66:67], v[84:85], v[66:67], v[84:85] op_sel_hi:[0,1,0]
	v_rcp_f32_e32 v76, v76
	v_rcp_f32_e32 v77, v77
	v_rcp_f32_e32 v66, v66
	v_rcp_f32_e32 v67, v67
	v_or_b32_e32 v78, 48, v171
	v_pk_mul_f32 v[74:75], v[74:75], v[86:87]
	v_pk_mul_f32 v[76:77], v[80:81], v[76:77]
	v_pk_mul_f32 v[72:73], v[72:73], v[66:67]
	v_cvt_pk_bf16_f32 v68, v70, v71
	v_mad_i64_i32 v[70:71], s[0:1], v78, s61, v[114:115]
	v_cvt_pk_bf16_f32 v66, v74, v75
	v_cvt_pk_bf16_f32 v67, v76, v77
	v_cvt_pk_bf16_f32 v69, v72, v73
	v_lshl_add_u64 v[70:71], v[70:71], 0, v[116:117]
	global_store_dwordx4 v[70:71], v[66:69], off sc1
	s_nop 1
	v_add_f32_e32 v66, v142, v143
	v_add_f32_e32 v68, v144, v145
	v_add_u32_e32 v67, 0x80, v171
	v_add_f32_e32 v66, v66, v68
	v_fmamk_f32 v66, v66, 0x3a800000, v191
	v_rsq_f32_e32 v68, v66
	s_nop 0
	v_mul_f32_e32 v66, 0xbfb8aa3b, v68
	v_mul_f32_e32 v68, v68, v68
	v_pk_mul_f32 v[70:71], v[58:59], v[66:67] op_sel_hi:[1,0]
	v_pk_mul_f32 v[58:59], v[58:59], v[62:63]
	v_pk_mul_f32 v[62:63], v[50:51], v[66:67] op_sel_hi:[1,0]
	v_rcp_f32_e32 v68, v68
	v_exp_f32_e32 v62, v62
	v_exp_f32_e32 v63, v63
	v_pk_mul_f32 v[50:51], v[50:51], v[54:55]
	v_pk_mul_f32 v[60:61], v[60:61], v[66:67] op_sel_hi:[1,0]
	v_exp_f32_e32 v70, v70
	v_pk_fma_f32 v[62:63], v[68:69], v[62:63], v[68:69] op_sel_hi:[0,1,0]
	v_rcp_f32_e32 v62, v62
	v_rcp_f32_e32 v63, v63
	v_exp_f32_e32 v71, v71
	v_exp_f32_e32 v60, v60
	v_exp_f32_e32 v61, v61
	v_pk_mul_f32 v[54:55], v[50:51], v[62:63]
	v_pk_mul_f32 v[50:51], v[52:53], v[66:67] op_sel_hi:[1,0]
	v_pk_fma_f32 v[70:71], v[68:69], v[70:71], v[68:69] op_sel_hi:[0,1,0]
	v_exp_f32_e32 v50, v50
	v_exp_f32_e32 v51, v51
	v_pk_fma_f32 v[60:61], v[68:69], v[60:61], v[68:69] op_sel_hi:[0,1,0]
	v_rcp_f32_e32 v70, v70
	v_rcp_f32_e32 v71, v71
	v_pk_fma_f32 v[50:51], v[68:69], v[50:51], v[68:69] op_sel_hi:[0,1,0]
	v_rcp_f32_e32 v60, v60
	v_rcp_f32_e32 v61, v61
	v_rcp_f32_e32 v50, v50
	v_rcp_f32_e32 v51, v51
	v_pk_mul_f32 v[58:59], v[58:59], v[70:71]
	v_pk_mul_f32 v[60:61], v[64:65], v[60:61]
	v_cvt_pk_bf16_f32 v52, v54, v55
	v_pk_mul_f32 v[56:57], v[56:57], v[50:51]
	v_mad_i64_i32 v[54:55], s[0:1], v67, s61, v[114:115]
	v_cvt_pk_bf16_f32 v50, v58, v59
	v_cvt_pk_bf16_f32 v51, v60, v61
	v_cvt_pk_bf16_f32 v53, v56, v57
	v_lshl_add_u64 v[54:55], v[54:55], 0, v[116:117]
	global_store_dwordx4 v[54:55], v[50:53], off sc1
	s_nop 1
	v_add_f32_e32 v50, v138, v139
	v_add_f32_e32 v51, v140, v141
	s_nop 0
	v_add_f32_e32 v50, v50, v51
	v_fmamk_f32 v50, v50, 0x3a800000, v191
	v_rsq_f32_e32 v51, v50
	s_nop 0
	v_mul_f32_e32 v50, 0xbfb8aa3b, v51
	v_mul_f32_e32 v51, v51, v51
	v_pk_mul_f32 v[54:55], v[40:41], v[50:51] op_sel_hi:[1,0]
	v_pk_mul_f32 v[40:41], v[40:41], v[44:45]
	v_pk_mul_f32 v[44:45], v[32:33], v[50:51] op_sel_hi:[1,0]
	v_rcp_f32_e32 v52, v51
	v_exp_f32_e32 v44, v44
	v_exp_f32_e32 v45, v45
	v_pk_mul_f32 v[32:33], v[32:33], v[36:37]
	v_pk_mul_f32 v[42:43], v[42:43], v[50:51] op_sel_hi:[1,0]
	v_exp_f32_e32 v54, v54
	v_pk_fma_f32 v[44:45], v[52:53], v[44:45], v[52:53] op_sel_hi:[0,1,0]
	v_rcp_f32_e32 v44, v44
	v_rcp_f32_e32 v45, v45
	v_exp_f32_e32 v55, v55
	v_exp_f32_e32 v42, v42
	v_exp_f32_e32 v43, v43
	v_pk_mul_f32 v[36:37], v[32:33], v[44:45]
	v_pk_mul_f32 v[32:33], v[34:35], v[50:51] op_sel_hi:[1,0]
	v_pk_fma_f32 v[54:55], v[52:53], v[54:55], v[52:53] op_sel_hi:[0,1,0]
	v_exp_f32_e32 v32, v32
	v_exp_f32_e32 v33, v33
	v_pk_fma_f32 v[42:43], v[52:53], v[42:43], v[52:53] op_sel_hi:[0,1,0]
	v_rcp_f32_e32 v54, v54
	v_rcp_f32_e32 v55, v55
	v_pk_fma_f32 v[32:33], v[52:53], v[32:33], v[52:53] op_sel_hi:[0,1,0]
	v_rcp_f32_e32 v42, v42
	v_rcp_f32_e32 v43, v43
	v_rcp_f32_e32 v32, v32
	v_rcp_f32_e32 v33, v33
	v_add_u32_e32 v44, 0x90, v171
	v_pk_mul_f32 v[40:41], v[40:41], v[54:55]
	v_pk_mul_f32 v[42:43], v[46:47], v[42:43]
	v_pk_mul_f32 v[38:39], v[38:39], v[32:33]
	v_cvt_pk_bf16_f32 v34, v36, v37
	v_mad_i64_i32 v[36:37], s[0:1], v44, s61, v[114:115]
	v_cvt_pk_bf16_f32 v32, v40, v41
	v_cvt_pk_bf16_f32 v33, v42, v43
	v_cvt_pk_bf16_f32 v35, v38, v39
	v_lshl_add_u64 v[36:37], v[36:37], 0, v[116:117]
	global_store_dwordx4 v[36:37], v[32:35], off sc1
	s_nop 1
	v_add_f32_e32 v32, v134, v135
	v_add_f32_e32 v33, v136, v137
	s_nop 0
	v_add_f32_e32 v32, v32, v33
	v_fmamk_f32 v32, v32, 0x3a800000, v191
	v_rsq_f32_e32 v33, v32
	s_nop 0
	v_mul_f32_e32 v32, 0xbfb8aa3b, v33
	v_mul_f32_e32 v33, v33, v33
	v_pk_mul_f32 v[36:37], v[24:25], v[32:33] op_sel_hi:[1,0]
	v_pk_mul_f32 v[24:25], v[24:25], v[28:29]
	v_pk_mul_f32 v[28:29], v[16:17], v[32:33] op_sel_hi:[1,0]
	v_rcp_f32_e32 v34, v33
	v_exp_f32_e32 v28, v28
	v_exp_f32_e32 v29, v29
	v_pk_mul_f32 v[16:17], v[16:17], v[20:21]
	v_pk_mul_f32 v[26:27], v[26:27], v[32:33] op_sel_hi:[1,0]
	v_exp_f32_e32 v36, v36
	v_pk_fma_f32 v[28:29], v[34:35], v[28:29], v[34:35] op_sel_hi:[0,1,0]
	v_rcp_f32_e32 v28, v28
	v_rcp_f32_e32 v29, v29
	v_exp_f32_e32 v37, v37
	v_exp_f32_e32 v26, v26
	v_exp_f32_e32 v27, v27
	v_pk_mul_f32 v[20:21], v[16:17], v[28:29]
	v_pk_mul_f32 v[16:17], v[18:19], v[32:33] op_sel_hi:[1,0]
	v_pk_fma_f32 v[36:37], v[34:35], v[36:37], v[34:35] op_sel_hi:[0,1,0]
	v_exp_f32_e32 v16, v16
	v_exp_f32_e32 v17, v17
	v_pk_fma_f32 v[26:27], v[34:35], v[26:27], v[34:35] op_sel_hi:[0,1,0]
	v_rcp_f32_e32 v36, v36
	v_rcp_f32_e32 v37, v37
	v_pk_fma_f32 v[16:17], v[34:35], v[16:17], v[34:35] op_sel_hi:[0,1,0]
	v_rcp_f32_e32 v26, v26
	v_rcp_f32_e32 v27, v27
	v_rcp_f32_e32 v16, v16
	v_rcp_f32_e32 v17, v17
	v_add_u32_e32 v28, 0xa0, v171
	v_pk_mul_f32 v[24:25], v[24:25], v[36:37]
	v_pk_mul_f32 v[26:27], v[30:31], v[26:27]
	v_pk_mul_f32 v[22:23], v[22:23], v[16:17]
	v_cvt_pk_bf16_f32 v18, v20, v21
	v_mad_i64_i32 v[20:21], s[0:1], v28, s61, v[114:115]
	v_cvt_pk_bf16_f32 v16, v24, v25
	v_cvt_pk_bf16_f32 v17, v26, v27
	v_cvt_pk_bf16_f32 v19, v22, v23
	v_lshl_add_u64 v[20:21], v[20:21], 0, v[116:117]
	global_store_dwordx4 v[20:21], v[16:19], off sc1
	s_nop 1
	v_add_f32_e32 v16, v126, v127
	v_add_f32_e32 v17, v128, v129
	s_nop 0
	v_add_f32_e32 v16, v16, v17
	v_fmamk_f32 v16, v16, 0x3a800000, v191
	v_rsq_f32_e32 v17, v16
	s_nop 0
	v_mul_f32_e32 v16, 0xbfb8aa3b, v17
	v_mul_f32_e32 v17, v17, v17
	v_pk_mul_f32 v[20:21], v[8:9], v[16:17] op_sel_hi:[1,0]
	v_pk_mul_f32 v[8:9], v[8:9], v[12:13]
	v_pk_mul_f32 v[12:13], v[0:1], v[16:17] op_sel_hi:[1,0]
	v_rcp_f32_e32 v18, v17
	v_exp_f32_e32 v12, v12
	v_exp_f32_e32 v13, v13
	v_pk_mul_f32 v[0:1], v[0:1], v[4:5]
	v_pk_mul_f32 v[10:11], v[10:11], v[16:17] op_sel_hi:[1,0]
	v_exp_f32_e32 v20, v20
	v_pk_fma_f32 v[12:13], v[18:19], v[12:13], v[18:19] op_sel_hi:[0,1,0]
	v_rcp_f32_e32 v12, v12
	v_rcp_f32_e32 v13, v13
	v_exp_f32_e32 v21, v21
	v_exp_f32_e32 v10, v10
	v_exp_f32_e32 v11, v11
	v_pk_mul_f32 v[4:5], v[0:1], v[12:13]
	v_pk_mul_f32 v[0:1], v[2:3], v[16:17] op_sel_hi:[1,0]
	v_pk_fma_f32 v[20:21], v[18:19], v[20:21], v[18:19] op_sel_hi:[0,1,0]
	v_exp_f32_e32 v0, v0
	v_exp_f32_e32 v1, v1
	v_pk_fma_f32 v[10:11], v[18:19], v[10:11], v[18:19] op_sel_hi:[0,1,0]
	v_rcp_f32_e32 v20, v20
	v_rcp_f32_e32 v21, v21
	v_pk_fma_f32 v[0:1], v[18:19], v[0:1], v[18:19] op_sel_hi:[0,1,0]
	v_rcp_f32_e32 v10, v10
	v_rcp_f32_e32 v11, v11
	v_rcp_f32_e32 v0, v0
	v_rcp_f32_e32 v1, v1
	v_add_u32_e32 v12, 0xb0, v171
	v_pk_mul_f32 v[8:9], v[8:9], v[20:21]
	v_pk_mul_f32 v[10:11], v[14:15], v[10:11]
	v_pk_mul_f32 v[6:7], v[6:7], v[0:1]
	v_cvt_pk_bf16_f32 v2, v4, v5
	v_mad_i64_i32 v[4:5], s[0:1], v12, s61, v[114:115]
	v_cvt_pk_bf16_f32 v0, v8, v9
	v_cvt_pk_bf16_f32 v1, v10, v11
	v_cvt_pk_bf16_f32 v3, v6, v7
	v_lshl_add_u64 v[4:5], v[4:5], 0, v[116:117]
	global_store_dwordx4 v[4:5], v[0:3], off sc1
	s_cbranch_vccnz .LBB0_150
	s_andn2_b64 vcc, exec, s[10:11]
	s_cbranch_vccnz .LBB0_164
	s_lshl_b32 s0, s85, 12
	s_and_b32 s0, s0, 0x1000
	s_add_i32 m0, s82, s0
	s_lshl_b32 s0, s22, 8
	s_add_i32 s0, s0, s83
	s_ashr_i32 s1, s0, 31
	v_lshl_add_u64 v[0:1], s[0:1], 4, v[160:161]
	global_load_lds_dwordx4 v[0:1], off

.LBB0_197:
	s_lshl_b32 s0, s0, 8
	v_lshl_or_b32 v132, s26, 8, v241
	v_add_u32_e32 v130, s0, v239
	v_ashrrev_i32_e32 v133, 31, v132
	v_lshlrev_b64 v[208:209], 1, v[132:133]
	v_ashrrev_i32_e32 v131, 31, v130
	v_lshl_add_u64 v[132:133], s[16:17], 0, v[208:209]
	v_lshlrev_b64 v[224:225], 11, v[130:131]
	v_lshl_add_u64 v[134:135], v[132:133], 0, v[224:225]
	global_load_dwordx4 v[248:251], v[134:135], off
	global_load_dwordx4 v[186:189], v[134:135], off offset:256
	v_or_b32_e32 v134, 16, v130
	v_ashrrev_i32_e32 v135, 31, v134
	v_lshlrev_b64 v[222:223], 11, v[134:135]
	v_lshl_add_u64 v[134:135], v[132:133], 0, v[222:223]
	global_load_dwordx4 v[182:185], v[134:135], off
	global_load_dwordx4 v[178:181], v[134:135], off offset:256
	v_or_b32_e32 v134, 32, v130
	v_ashrrev_i32_e32 v135, 31, v134
	v_lshlrev_b64 v[220:221], 11, v[134:135]
	v_lshl_add_u64 v[134:135], v[132:133], 0, v[220:221]
	global_load_dwordx4 v[174:177], v[134:135], off
	global_load_dwordx4 v[170:173], v[134:135], off offset:256
	v_or_b32_e32 v130, 48, v130
	v_ashrrev_i32_e32 v131, 31, v130
	v_lshlrev_b64 v[218:219], 11, v[130:131]
	v_lshl_add_u64 v[130:131], v[132:133], 0, v[218:219]
	global_load_dwordx4 v[166:169], v[130:131], off
	global_load_dwordx4 v[162:165], v[130:131], off offset:256
	s_mov_b64 s[30:31], 0x40000
	v_lshl_add_u64 v[216:217], v[224:225], 0, s[30:31]
	v_lshl_add_u64 v[130:131], v[132:133], 0, v[216:217]
	global_load_dwordx4 v[158:161], v[130:131], off
	global_load_dwordx4 v[154:157], v[130:131], off offset:256
	s_mov_b64 s[30:31], 0x48000
	v_lshl_add_u64 v[214:215], v[224:225], 0, s[30:31]
	v_lshl_add_u64 v[130:131], v[132:133], 0, v[214:215]
	global_load_dwordx4 v[150:153], v[130:131], off
	global_load_dwordx4 v[146:149], v[130:131], off offset:256
	s_mov_b64 s[30:31], 0x50000
	v_lshl_add_u64 v[212:213], v[224:225], 0, s[30:31]
	s_mov_b64 s[30:31], 0x58000
	v_lshl_add_u64 v[130:131], v[132:133], 0, v[212:213]
	v_lshl_add_u64 v[210:211], v[224:225], 0, s[30:31]
	global_load_dwordx4 v[142:145], v[130:131], off
	global_load_dwordx4 v[138:141], v[130:131], off offset:256
	v_lshl_add_u64 v[130:131], v[132:133], 0, v[210:211]
	global_load_dwordx4 v[134:137], v[130:131], off
	s_nop 0
	global_load_dwordx4 v[130:133], v[130:131], off offset:256
	s_waitcnt vmcnt(0)
	v_lshlrev_b32_e32 v252, 16, v248
	v_and_b32_e32 v253, 0xffff0000, v248
	v_lshlrev_b32_e32 v248, 16, v249
	v_and_b32_e32 v249, 0xffff0000, v249
	v_pk_add_f32 v[128:129], v[128:129], v[248:249]
	v_pk_add_f32 v[126:127], v[126:127], v[252:253]
	v_pk_mul_f32 v[248:249], v[128:129], v[128:129]
	v_lshlrev_b32_e32 v252, 16, v250
	v_and_b32_e32 v253, 0xffff0000, v250
	v_pk_fma_f32 v[248:249], v[126:127], v[126:127], v[248:249]
	v_pk_add_f32 v[252:253], v[122:123], v[252:253]
	s_nop 0
	v_pk_fma_f32 v[122:123], v[252:253], v[252:253], v[248:249]
	v_lshlrev_b32_e32 v248, 16, v251
	v_and_b32_e32 v249, 0xffff0000, v251
	v_pk_add_f32 v[248:249], v[124:125], v[248:249]
	v_cvt_pk_bf16_f32 v124, v252, v253
	v_pk_fma_f32 v[250:251], v[248:249], v[248:249], v[122:123]
	v_cvt_pk_bf16_f32 v122, v126, v127
	v_lshl_add_u64 v[126:127], s[20:21], 0, v[224:225]
	v_cvt_pk_bf16_f32 v123, v128, v129
	v_cvt_pk_bf16_f32 v125, v248, v249
	v_lshl_add_u64 v[126:127], v[126:127], 0, v[208:209]
	global_store_dwordx4 v[126:127], v[122:125], off sc1
	s_nop 1
	v_lshlrev_b32_e32 v122, 16, v186
	v_and_b32_e32 v123, 0xffff0000, v186
	v_pk_add_f32 v[118:119], v[118:119], v[122:123]
	v_lshlrev_b32_e32 v124, 16, v187
	v_and_b32_e32 v125, 0xffff0000, v187
	v_pk_fma_f32 v[122:123], v[118:119], v[118:119], v[250:251]
	v_pk_add_f32 v[120:121], v[120:121], v[124:125]
	v_lshlrev_b32_e32 v124, 16, v188
	v_and_b32_e32 v125, 0xffff0000, v188
	v_pk_fma_f32 v[122:123], v[120:121], v[120:121], v[122:123]
	v_pk_add_f32 v[124:125], v[114:115], v[124:125]
	s_nop 0
	v_pk_fma_f32 v[114:115], v[124:125], v[124:125], v[122:123]
	v_lshlrev_b32_e32 v122, 16, v189
	v_and_b32_e32 v123, 0xffff0000, v189
	v_pk_add_f32 v[122:123], v[116:117], v[122:123]
	v_cvt_pk_bf16_f32 v116, v124, v125
	v_pk_fma_f32 v[128:129], v[122:123], v[122:123], v[114:115]
	v_cvt_pk_bf16_f32 v114, v118, v119
	v_cvt_pk_bf16_f32 v115, v120, v121
	v_cvt_pk_bf16_f32 v117, v122, v123
	global_store_dwordx4 v[126:127], v[114:117], off offset:256 sc1
	v_lshlrev_b32_e32 v118, 16, v184
	v_and_b32_e32 v119, 0xffff0000, v184
	v_lshlrev_b32_e32 v116, 16, v182
	v_and_b32_e32 v117, 0xffff0000, v182
	v_pk_add_f32 v[110:111], v[110:111], v[116:117]
	v_lshlrev_b32_e32 v116, 16, v183
	v_and_b32_e32 v117, 0xffff0000, v183
	v_pk_add_f32 v[112:113], v[112:113], v[116:117]
	v_pk_add_f32 v[118:119], v[98:99], v[118:119]
	v_pk_mul_f32 v[116:117], v[112:113], v[112:113]
	v_add_f32_e32 v114, v128, v129
	v_pk_fma_f32 v[116:117], v[110:111], v[110:111], v[116:117]
	s_nop 0
	v_pk_fma_f32 v[98:99], v[118:119], v[118:119], v[116:117]
	v_lshlrev_b32_e32 v116, 16, v185
	v_and_b32_e32 v117, 0xffff0000, v185
	v_pk_add_f32 v[116:117], v[100:101], v[116:117]
	v_cvt_pk_bf16_f32 v100, v118, v119
	v_pk_fma_f32 v[120:121], v[116:117], v[116:117], v[98:99]
	v_cvt_pk_bf16_f32 v98, v110, v111
	v_lshl_add_u64 v[110:111], s[20:21], 0, v[222:223]
	v_cvt_pk_bf16_f32 v99, v112, v113
	v_cvt_pk_bf16_f32 v101, v116, v117
	v_lshl_add_u64 v[110:111], v[110:111], 0, v[208:209]
	global_store_dwordx4 v[110:111], v[98:101], off sc1
	s_nop 1
	v_lshlrev_b32_e32 v98, 16, v178
	v_and_b32_e32 v99, 0xffff0000, v178
	v_pk_add_f32 v[98:99], v[106:107], v[98:99]
	v_lshlrev_b32_e32 v106, 16, v179
	v_and_b32_e32 v107, 0xffff0000, v179
	v_pk_fma_f32 v[100:101], v[98:99], v[98:99], v[120:121]
	v_pk_add_f32 v[106:107], v[108:109], v[106:107]
	v_lshlrev_b32_e32 v108, 16, v180
	v_and_b32_e32 v109, 0xffff0000, v180
	v_pk_fma_f32 v[100:101], v[106:107], v[106:107], v[100:101]
	v_pk_add_f32 v[102:103], v[102:103], v[108:109]
	v_lshlrev_b32_e32 v108, 16, v181
	v_and_b32_e32 v109, 0xffff0000, v181
	v_pk_fma_f32 v[100:101], v[102:103], v[102:103], v[100:101]
	v_pk_add_f32 v[104:105], v[104:105], v[108:109]
	v_cvt_pk_bf16_f32 v98, v98, v99
	v_pk_fma_f32 v[108:109], v[104:105], v[104:105], v[100:101]
	v_cvt_pk_bf16_f32 v99, v106, v107
	v_cvt_pk_bf16_f32 v100, v102, v103
	v_cvt_pk_bf16_f32 v101, v104, v105
	global_store_dwordx4 v[110:111], v[98:101], off offset:256 sc1
	v_add_f32_e32 v104, v108, v109
	s_nop 0
	v_lshlrev_b32_e32 v98, 16, v174
	v_and_b32_e32 v99, 0xffff0000, v174
	v_pk_add_f32 v[94:95], v[94:95], v[98:99]
	v_lshlrev_b32_e32 v98, 16, v175
	v_and_b32_e32 v99, 0xffff0000, v175
	v_pk_add_f32 v[96:97], v[96:97], v[98:99]
	v_lshlrev_b32_e32 v100, 16, v176
	v_pk_mul_f32 v[98:99], v[96:97], v[96:97]
	v_and_b32_e32 v101, 0xffff0000, v176
	v_pk_fma_f32 v[98:99], v[94:95], v[94:95], v[98:99]
	v_pk_add_f32 v[100:101], v[82:83], v[100:101]
	s_nop 0
	v_pk_fma_f32 v[82:83], v[100:101], v[100:101], v[98:99]
	v_lshlrev_b32_e32 v98, 16, v177
	v_and_b32_e32 v99, 0xffff0000, v177
	v_pk_add_f32 v[98:99], v[84:85], v[98:99]
	v_cvt_pk_bf16_f32 v84, v100, v101
	v_pk_fma_f32 v[102:103], v[98:99], v[98:99], v[82:83]
	v_cvt_pk_bf16_f32 v82, v94, v95
	v_lshl_add_u64 v[94:95], s[20:21], 0, v[220:221]
	v_cvt_pk_bf16_f32 v83, v96, v97
	v_cvt_pk_bf16_f32 v85, v98, v99
	v_lshl_add_u64 v[94:95], v[94:95], 0, v[208:209]
	global_store_dwordx4 v[94:95], v[82:85], off sc1
	s_nop 1
	v_lshlrev_b32_e32 v82, 16, v170
	v_and_b32_e32 v83, 0xffff0000, v170
	v_pk_add_f32 v[82:83], v[90:91], v[82:83]
	v_lshlrev_b32_e32 v90, 16, v171
	v_and_b32_e32 v91, 0xffff0000, v171
	v_pk_fma_f32 v[84:85], v[82:83], v[82:83], v[102:103]
	v_pk_add_f32 v[90:91], v[92:93], v[90:91]
	v_lshlrev_b32_e32 v92, 16, v172
	v_and_b32_e32 v93, 0xffff0000, v172
	v_pk_fma_f32 v[84:85], v[90:91], v[90:91], v[84:85]
	v_pk_add_f32 v[86:87], v[86:87], v[92:93]
	v_lshlrev_b32_e32 v92, 16, v173
	v_and_b32_e32 v93, 0xffff0000, v173
	v_pk_fma_f32 v[84:85], v[86:87], v[86:87], v[84:85]
	v_pk_add_f32 v[88:89], v[88:89], v[92:93]
	v_cvt_pk_bf16_f32 v82, v82, v83
	v_pk_fma_f32 v[92:93], v[88:89], v[88:89], v[84:85]
	v_cvt_pk_bf16_f32 v83, v90, v91
	v_cvt_pk_bf16_f32 v84, v86, v87
	v_cvt_pk_bf16_f32 v85, v88, v89
	global_store_dwordx4 v[94:95], v[82:85], off offset:256 sc1
	v_add_f32_e32 v88, v92, v93
	s_nop 0
	v_lshlrev_b32_e32 v82, 16, v166
	v_and_b32_e32 v83, 0xffff0000, v166
	v_pk_add_f32 v[78:79], v[78:79], v[82:83]
	v_lshlrev_b32_e32 v82, 16, v167
	v_and_b32_e32 v83, 0xffff0000, v167
	v_pk_add_f32 v[80:81], v[80:81], v[82:83]
	v_lshlrev_b32_e32 v84, 16, v168
	v_pk_mul_f32 v[82:83], v[80:81], v[80:81]
	v_and_b32_e32 v85, 0xffff0000, v168
	v_pk_fma_f32 v[82:83], v[78:79], v[78:79], v[82:83]
	v_pk_add_f32 v[84:85], v[66:67], v[84:85]
	s_nop 0
	v_pk_fma_f32 v[66:67], v[84:85], v[84:85], v[82:83]
	v_lshlrev_b32_e32 v82, 16, v169
	v_and_b32_e32 v83, 0xffff0000, v169
	v_pk_add_f32 v[82:83], v[68:69], v[82:83]
	v_cvt_pk_bf16_f32 v68, v84, v85
	v_pk_fma_f32 v[86:87], v[82:83], v[82:83], v[66:67]
	v_cvt_pk_bf16_f32 v66, v78, v79
	v_lshl_add_u64 v[78:79], s[20:21], 0, v[218:219]
	v_cvt_pk_bf16_f32 v67, v80, v81
	v_cvt_pk_bf16_f32 v69, v82, v83
	v_lshl_add_u64 v[78:79], v[78:79], 0, v[208:209]
	global_store_dwordx4 v[78:79], v[66:69], off sc1
	s_nop 1
	v_lshlrev_b32_e32 v66, 16, v162
	v_and_b32_e32 v67, 0xffff0000, v162
	v_pk_add_f32 v[66:67], v[74:75], v[66:67]
	v_lshlrev_b32_e32 v74, 16, v163
	v_and_b32_e32 v75, 0xffff0000, v163
	v_pk_fma_f32 v[68:69], v[66:67], v[66:67], v[86:87]
	v_pk_add_f32 v[74:75], v[76:77], v[74:75]
	v_lshlrev_b32_e32 v76, 16, v164
	v_and_b32_e32 v77, 0xffff0000, v164
	v_pk_fma_f32 v[68:69], v[74:75], v[74:75], v[68:69]
	v_pk_add_f32 v[70:71], v[70:71], v[76:77]
	v_lshlrev_b32_e32 v76, 16, v165
	v_and_b32_e32 v77, 0xffff0000, v165
	v_pk_fma_f32 v[68:69], v[70:71], v[70:71], v[68:69]
	v_pk_add_f32 v[72:73], v[72:73], v[76:77]
	v_cvt_pk_bf16_f32 v66, v66, v67
	v_pk_fma_f32 v[76:77], v[72:73], v[72:73], v[68:69]
	v_cvt_pk_bf16_f32 v67, v74, v75
	v_cvt_pk_bf16_f32 v68, v70, v71
	v_cvt_pk_bf16_f32 v69, v72, v73
	global_store_dwordx4 v[78:79], v[66:69], off offset:256 sc1
	v_add_f32_e32 v72, v76, v77
	s_nop 0
	v_lshlrev_b32_e32 v66, 16, v158
	v_and_b32_e32 v67, 0xffff0000, v158
	v_pk_add_f32 v[62:63], v[62:63], v[66:67]
	v_lshlrev_b32_e32 v66, 16, v159
	v_and_b32_e32 v67, 0xffff0000, v159
	v_pk_add_f32 v[64:65], v[64:65], v[66:67]
	v_lshlrev_b32_e32 v68, 16, v160
	v_pk_mul_f32 v[66:67], v[64:65], v[64:65]
	v_and_b32_e32 v69, 0xffff0000, v160
	v_pk_fma_f32 v[66:67], v[62:63], v[62:63], v[66:67]
	v_pk_add_f32 v[68:69], v[50:51], v[68:69]
	s_nop 0
	v_pk_fma_f32 v[50:51], v[68:69], v[68:69], v[66:67]
	v_lshlrev_b32_e32 v66, 16, v161
	v_and_b32_e32 v67, 0xffff0000, v161
	v_pk_add_f32 v[66:67], v[52:53], v[66:67]
	v_cvt_pk_bf16_f32 v52, v68, v69
	v_pk_fma_f32 v[70:71], v[66:67], v[66:67], v[50:51]
	v_cvt_pk_bf16_f32 v50, v62, v63
	v_lshl_add_u64 v[62:63], s[20:21], 0, v[216:217]
	v_cvt_pk_bf16_f32 v51, v64, v65
	v_cvt_pk_bf16_f32 v53, v66, v67
	v_lshl_add_u64 v[62:63], v[62:63], 0, v[208:209]
	global_store_dwordx4 v[62:63], v[50:53], off sc1
	s_nop 1
	v_lshlrev_b32_e32 v50, 16, v154
	v_and_b32_e32 v51, 0xffff0000, v154
	v_pk_add_f32 v[50:51], v[58:59], v[50:51]
	v_lshlrev_b32_e32 v58, 16, v155
	v_and_b32_e32 v59, 0xffff0000, v155
	v_pk_fma_f32 v[52:53], v[50:51], v[50:51], v[70:71]
	v_pk_add_f32 v[58:59], v[60:61], v[58:59]
	v_lshlrev_b32_e32 v60, 16, v156
	v_and_b32_e32 v61, 0xffff0000, v156
	v_pk_fma_f32 v[52:53], v[58:59], v[58:59], v[52:53]
	v_pk_add_f32 v[54:55], v[54:55], v[60:61]
	v_lshlrev_b32_e32 v60, 16, v157
	v_and_b32_e32 v61, 0xffff0000, v157
	v_pk_fma_f32 v[52:53], v[54:55], v[54:55], v[52:53]
	v_pk_add_f32 v[56:57], v[56:57], v[60:61]
	v_cvt_pk_bf16_f32 v50, v50, v51
	v_pk_fma_f32 v[60:61], v[56:57], v[56:57], v[52:53]
	v_cvt_pk_bf16_f32 v51, v58, v59
	v_cvt_pk_bf16_f32 v52, v54, v55
	v_cvt_pk_bf16_f32 v53, v56, v57
	global_store_dwordx4 v[62:63], v[50:53], off offset:256 sc1
	v_add_f32_e32 v56, v60, v61
	s_nop 0
	v_lshlrev_b32_e32 v50, 16, v150
	v_and_b32_e32 v51, 0xffff0000, v150
	v_pk_add_f32 v[44:45], v[44:45], v[50:51]
	v_lshlrev_b32_e32 v50, 16, v151
	v_and_b32_e32 v51, 0xffff0000, v151
	v_pk_add_f32 v[46:47], v[46:47], v[50:51]
	v_lshlrev_b32_e32 v52, 16, v152
	v_pk_mul_f32 v[50:51], v[46:47], v[46:47]
	v_and_b32_e32 v53, 0xffff0000, v152
	v_pk_fma_f32 v[50:51], v[44:45], v[44:45], v[50:51]
	v_pk_add_f32 v[52:53], v[32:33], v[52:53]
	s_nop 0
	v_pk_fma_f32 v[32:33], v[52:53], v[52:53], v[50:51]
	v_lshlrev_b32_e32 v50, 16, v153
	v_and_b32_e32 v51, 0xffff0000, v153
	v_pk_add_f32 v[50:51], v[34:35], v[50:51]
	v_cvt_pk_bf16_f32 v34, v52, v53
	v_pk_fma_f32 v[54:55], v[50:51], v[50:51], v[32:33]
	v_cvt_pk_bf16_f32 v32, v44, v45
	v_lshl_add_u64 v[44:45], s[20:21], 0, v[214:215]
	v_cvt_pk_bf16_f32 v33, v46, v47
	v_cvt_pk_bf16_f32 v35, v50, v51
	v_lshl_add_u64 v[44:45], v[44:45], 0, v[208:209]
	global_store_dwordx4 v[44:45], v[32:35], off sc1
	s_nop 1
	v_lshlrev_b32_e32 v32, 16, v146
	v_and_b32_e32 v33, 0xffff0000, v146
	v_pk_add_f32 v[32:33], v[40:41], v[32:33]
	v_lshlrev_b32_e32 v40, 16, v147
	v_and_b32_e32 v41, 0xffff0000, v147
	v_pk_fma_f32 v[34:35], v[32:33], v[32:33], v[54:55]
	v_pk_add_f32 v[40:41], v[42:43], v[40:41]
	v_lshlrev_b32_e32 v42, 16, v148
	v_and_b32_e32 v43, 0xffff0000, v148
	v_pk_fma_f32 v[34:35], v[40:41], v[40:41], v[34:35]
	v_pk_add_f32 v[36:37], v[36:37], v[42:43]
	v_lshlrev_b32_e32 v42, 16, v149
	v_and_b32_e32 v43, 0xffff0000, v149
	v_pk_fma_f32 v[34:35], v[36:37], v[36:37], v[34:35]
	v_pk_add_f32 v[38:39], v[38:39], v[42:43]
	v_cvt_pk_bf16_f32 v32, v32, v33
	v_pk_fma_f32 v[42:43], v[38:39], v[38:39], v[34:35]
	v_cvt_pk_bf16_f32 v33, v40, v41
	v_cvt_pk_bf16_f32 v34, v36, v37
	v_cvt_pk_bf16_f32 v35, v38, v39
	global_store_dwordx4 v[44:45], v[32:35], off offset:256 sc1
	v_add_f32_e32 v38, v42, v43
	s_nop 0
	v_lshlrev_b32_e32 v32, 16, v142
	v_and_b32_e32 v33, 0xffff0000, v142
	v_pk_add_f32 v[28:29], v[28:29], v[32:33]
	v_lshlrev_b32_e32 v32, 16, v143
	v_and_b32_e32 v33, 0xffff0000, v143
	v_pk_add_f32 v[30:31], v[30:31], v[32:33]
	v_lshlrev_b32_e32 v34, 16, v144
	v_pk_mul_f32 v[32:33], v[30:31], v[30:31]
	v_and_b32_e32 v35, 0xffff0000, v144
	v_pk_fma_f32 v[32:33], v[28:29], v[28:29], v[32:33]
	v_pk_add_f32 v[34:35], v[16:17], v[34:35]
	s_nop 0
	v_pk_fma_f32 v[16:17], v[34:35], v[34:35], v[32:33]
	v_lshlrev_b32_e32 v32, 16, v145
	v_and_b32_e32 v33, 0xffff0000, v145
	v_pk_add_f32 v[32:33], v[18:19], v[32:33]
	v_cvt_pk_bf16_f32 v18, v34, v35
	v_pk_fma_f32 v[36:37], v[32:33], v[32:33], v[16:17]
	v_cvt_pk_bf16_f32 v16, v28, v29
	v_lshl_add_u64 v[28:29], s[20:21], 0, v[212:213]
	v_cvt_pk_bf16_f32 v17, v30, v31
	v_cvt_pk_bf16_f32 v19, v32, v33
	v_lshl_add_u64 v[28:29], v[28:29], 0, v[208:209]
	global_store_dwordx4 v[28:29], v[16:19], off sc1
	s_nop 1
	v_lshlrev_b32_e32 v16, 16, v138
	v_and_b32_e32 v17, 0xffff0000, v138
	v_pk_add_f32 v[16:17], v[24:25], v[16:17]
	v_lshlrev_b32_e32 v24, 16, v139
	v_and_b32_e32 v25, 0xffff0000, v139
	v_pk_fma_f32 v[18:19], v[16:17], v[16:17], v[36:37]
	v_pk_add_f32 v[24:25], v[26:27], v[24:25]
	v_lshlrev_b32_e32 v26, 16, v140
	v_and_b32_e32 v27, 0xffff0000, v140
	v_pk_fma_f32 v[18:19], v[24:25], v[24:25], v[18:19]
	v_pk_add_f32 v[20:21], v[20:21], v[26:27]
	v_lshlrev_b32_e32 v26, 16, v141
	v_and_b32_e32 v27, 0xffff0000, v141
	v_pk_fma_f32 v[18:19], v[20:21], v[20:21], v[18:19]
	v_pk_add_f32 v[22:23], v[22:23], v[26:27]
	v_cvt_pk_bf16_f32 v16, v16, v17
	v_pk_fma_f32 v[26:27], v[22:23], v[22:23], v[18:19]
	v_cvt_pk_bf16_f32 v17, v24, v25
	v_cvt_pk_bf16_f32 v18, v20, v21
	v_cvt_pk_bf16_f32 v19, v22, v23
	global_store_dwordx4 v[28:29], v[16:19], off offset:256 sc1
	v_add_f32_e32 v22, v26, v27
	s_nop 0
	v_lshlrev_b32_e32 v16, 16, v134
	v_and_b32_e32 v17, 0xffff0000, v134
	v_pk_add_f32 v[12:13], v[12:13], v[16:17]
	v_lshlrev_b32_e32 v16, 16, v135
	v_and_b32_e32 v17, 0xffff0000, v135
	v_pk_add_f32 v[14:15], v[14:15], v[16:17]
	v_lshlrev_b32_e32 v18, 16, v136
	v_pk_mul_f32 v[16:17], v[14:15], v[14:15]
	v_and_b32_e32 v19, 0xffff0000, v136
	v_pk_fma_f32 v[16:17], v[12:13], v[12:13], v[16:17]
	v_pk_add_f32 v[18:19], v[0:1], v[18:19]
	s_nop 0
	v_pk_fma_f32 v[0:1], v[18:19], v[18:19], v[16:17]
	v_lshlrev_b32_e32 v16, 16, v137
	v_and_b32_e32 v17, 0xffff0000, v137
	v_pk_add_f32 v[16:17], v[2:3], v[16:17]
	v_cvt_pk_bf16_f32 v2, v18, v19
	v_pk_fma_f32 v[20:21], v[16:17], v[16:17], v[0:1]
	v_cvt_pk_bf16_f32 v0, v12, v13
	v_lshl_add_u64 v[12:13], s[20:21], 0, v[210:211]
	v_cvt_pk_bf16_f32 v1, v14, v15
	v_cvt_pk_bf16_f32 v3, v16, v17
	v_lshl_add_u64 v[12:13], v[12:13], 0, v[208:209]
	global_store_dwordx4 v[12:13], v[0:3], off sc1
	s_nop 1
	v_lshlrev_b32_e32 v0, 16, v130
	v_and_b32_e32 v1, 0xffff0000, v130
	v_pk_add_f32 v[0:1], v[8:9], v[0:1]
	v_lshlrev_b32_e32 v8, 16, v131
	v_and_b32_e32 v9, 0xffff0000, v131
	v_pk_fma_f32 v[2:3], v[0:1], v[0:1], v[20:21]
	v_pk_add_f32 v[8:9], v[10:11], v[8:9]
	v_lshlrev_b32_e32 v10, 16, v132
	v_and_b32_e32 v11, 0xffff0000, v132
	v_pk_fma_f32 v[2:3], v[8:9], v[8:9], v[2:3]
	v_pk_add_f32 v[4:5], v[4:5], v[10:11]
	v_lshlrev_b32_e32 v10, 16, v133
	v_and_b32_e32 v11, 0xffff0000, v133
	v_pk_fma_f32 v[2:3], v[4:5], v[4:5], v[2:3]
	v_pk_add_f32 v[6:7], v[6:7], v[10:11]
	v_cvt_pk_bf16_f32 v0, v0, v1
	v_pk_fma_f32 v[10:11], v[6:7], v[6:7], v[2:3]
	v_cvt_pk_bf16_f32 v1, v8, v9
	v_cvt_pk_bf16_f32 v2, v4, v5
	v_cvt_pk_bf16_f32 v3, v6, v7
	global_store_dwordx4 v[12:13], v[0:3], off offset:256 sc1
	s_nop 1
	v_and_b32_e32 v2, 64, v228
	v_xor_b32_e32 v1, 16, v228
	v_add_u32_e32 v8, 64, v2
	v_cmp_lt_i32_e32 vcc, v1, v8
	v_add_f32_e32 v0, v10, v11
	s_nop 0
	v_cndmask_b32_e32 v1, v228, v1, vcc
	v_lshlrev_b32_e32 v1, 2, v1
	ds_bpermute_b32 v3, v1, v104
	ds_bpermute_b32 v9, v1, v56
	ds_bpermute_b32 v2, v1, v114
	ds_bpermute_b32 v4, v1, v88
	ds_bpermute_b32 v5, v1, v72
	ds_bpermute_b32 v10, v1, v38
	ds_bpermute_b32 v11, v1, v22
	ds_bpermute_b32 v12, v1, v0
	s_waitcnt lgkmcnt(7)
	v_add_f32_e32 v7, v104, v3
	s_waitcnt lgkmcnt(6)
	v_add_f32_e32 v3, v56, v9
	v_xor_b32_e32 v9, 32, v228
	v_cmp_lt_i32_e32 vcc, v9, v8
	s_waitcnt lgkmcnt(5)
	v_add_f32_e32 v6, v114, v2
	s_waitcnt lgkmcnt(4)
	v_add_f32_e32 v4, v88, v4
	v_cndmask_b32_e32 v8, v228, v9, vcc
	s_waitcnt lgkmcnt(3)
	v_add_f32_e32 v5, v72, v5
	s_waitcnt lgkmcnt(2)
	v_add_f32_e32 v2, v38, v10
	s_waitcnt lgkmcnt(1)
	v_add_f32_e32 v1, v22, v11
	s_waitcnt lgkmcnt(0)
	v_add_f32_e32 v0, v0, v12
	v_lshlrev_b32_e32 v8, 2, v8
	ds_bpermute_b32 v14, v8, v6
	ds_bpermute_b32 v15, v8, v7
	ds_bpermute_b32 v12, v8, v4
	ds_bpermute_b32 v13, v8, v5
	ds_bpermute_b32 v11, v8, v3
	ds_bpermute_b32 v10, v8, v2
	ds_bpermute_b32 v9, v8, v1
	ds_bpermute_b32 v8, v8, v0
	s_and_saveexec_b64 s[30:31], s[8:9]
	s_cbranch_execz .LBB0_199
	s_waitcnt lgkmcnt(7)
	v_add_f32_e32 v6, v6, v14
	s_waitcnt lgkmcnt(6)
	v_add_f32_e32 v7, v7, v15
	s_waitcnt lgkmcnt(5)
	v_add_f32_e32 v4, v4, v12
	s_waitcnt lgkmcnt(4)
	v_add_f32_e32 v5, v5, v13
	s_waitcnt lgkmcnt(3)
	v_add_f32_e32 v3, v3, v11
	s_waitcnt lgkmcnt(2)
	v_add_f32_e32 v2, v2, v10
	s_waitcnt lgkmcnt(1)
	v_add_f32_e32 v1, v1, v9
	s_waitcnt lgkmcnt(0)
	v_add_f32_e32 v0, v0, v8
	ds_write2st64_b32 v243, v6, v7 offset1:1
	ds_write2st64_b32 v243, v4, v5 offset0:2 offset1:3
	ds_write_b32 v244, v3
	ds_write_b32 v245, v2
	ds_write_b32 v246, v1
	ds_write_b32 v247, v0
